# merge: gate sigmoid VALU interleaved into the branch-GEMM MFMA gaps (K-loop fully unrolled, 8 stages)
# speedup vs baseline: 1.0010x; 1.0010x over previous
; __device__ __forceinline__ int tid_opaque() { int t = threadIdx.x; asm volatile("" : "+v"(t)); return t; }
; #define ZERO_ACC(acc, MI_, NI_)                 \
;   _Pragma("unroll") for (int mi = 0; mi < MI_; ++mi) \
;   _Pragma("unroll") for (int ni = 0; ni < NI_; ++ni) \
;   _Pragma("unroll") for (int e = 0; e < 16; ++e) acc[mi][ni][e] = 0.f;
; template <int MI, int NI>
; __device__ __forceinline__ void gemm_kloop(const bf16* __restrict__ A, size_t lda, const bf16* __restrict__ Bt, size_t ldb, int K,
;                                            f16v (&acc)[MI][NI], bf16* sA, bf16* sB) {
;   const int tid = tid_opaque(), lane = tid & 63, w = tid >> 6;
;   const int r = lane & 31, hh = lane >> 5;
;   const int wm = w >> 1, wn = w & 1;
;   const int lrow = tid >> 3, lseg = tid & 7;
;   u4v ra[2 * MI], rb[2 * NI];
;   const int KT = K >> 6;
; #pragma unroll
;   for (int i = 0; i < 2 * MI; ++i) ra[i] = *(const u4v*)(A + (size_t)(lrow + 32 * i) * lda + lseg * 8);
; #pragma unroll
;   for (int i = 0; i < 2 * NI; ++i) rb[i] = *(const u4v*)(Bt + (size_t)(lrow + 32 * i) * ldb + lseg * 8);
; __device__ __forceinline__ void merge_tile(const Params& p, int mt, int nt, bf16* sA, bf16* sB) {
;     ...
;     f16v ap[2][2];
;     ZERO_ACC(ap, 2, 2)
;     const bf16* ya = b == 0 ? p.q : (b == 1 ? p.hv : p.gog);
;     gemm_kloop<2, 2>(ya + (size_t)m0 * 512, 512, p.WbT + (size_t)(b * 1024 + n0) * 512, 512, 512, ap, sA, sB);
.LBB0_1074:
	s_load_dwordx2 s[38:39], s[38:39], 0x0
	v_mov_b32_e32 v64, v195
	s_waitcnt lgkmcnt(0)
	s_add_u32 s40, s38, s22
	v_ashrrev_i32_e32 v50, 3, v64
	v_lshlrev_b32_e32 v0, 4, v64
	s_addc_u32 s41, s39, s23
	v_and_b32_e32 v0, 0x70, v0
	v_ashrrev_i32_e32 v51, 31, v50
	v_lshl_add_u64 v[52:53], s[40:41], 0, v[0:1]
	v_lshlrev_b64 v[54:55], 10, v[50:51]
	s_mov_b64 s[40:41], 0x8000
	v_lshl_add_u64 v[56:57], v[52:53], 0, v[54:55]
	v_lshl_add_u64 v[58:59], v[54:55], 0, s[40:41]
	s_mov_b64 s[40:41], 0x10000
	s_lshl_b64 s[36:37], s[36:37], 10
	v_lshl_add_u64 v[60:61], v[52:53], 0, v[58:59]
	v_lshl_add_u64 v[56:57], v[54:55], 0, s[40:41]
	s_mov_b64 s[40:41], 0x18000
	s_add_u32 s36, s14, s36
	v_lshl_add_u64 v[62:63], v[54:55], 0, s[40:41]
	s_addc_u32 s37, s15, s37
	v_lshl_add_u64 v[60:61], v[52:53], 0, v[56:57]
	v_lshl_add_u64 v[52:53], v[52:53], 0, v[62:63]
	v_lshl_add_u64 v[52:53], s[36:37], 0, v[0:1]
	v_lshl_add_u64 v[60:61], v[52:53], 0, v[54:55]
	v_lshl_add_u64 v[56:57], v[52:53], 0, v[56:57]
	v_lshl_add_u64 v[58:59], v[52:53], 0, v[58:59]
	v_lshl_add_u64 v[52:53], v[52:53], 0, v[62:63]
	v_and_b32_e32 v51, 31, v64
	v_lshrrev_b32_e32 v52, 1, v64
	s_mov_b32 s36, 0xfffffc0
	v_and_or_b32 v51, v52, s36, v51
	v_and_b32_e32 v53, 0x5f, v64
	s_add_u32 s36, s38, s30
	v_and_b32_e32 v52, 16, v52
	v_mul_lo_u32 v56, v50, s33
	v_mul_lo_u32 v51, v51, s33
	v_mul_u32_u24_e32 v53, 0x90, v53
	s_addc_u32 s37, s39, s31
	v_or_b32_e32 v54, v54, v0
	v_mov_b32_e32 v50, 0
	v_lshl_add_u64 v[162:163], s[36:37], 0, v[54:55]
	v_lshl_add_u64 v[164:165], s[34:35], 0, v[54:55]
	s_mov_b64 s[36:37], 0
	v_add_u32_e32 v204, v0, v56
	v_add_u32_e32 v0, v52, v51
	v_add_u32_e32 v203, v52, v53
	v_mov_b32_e32 v51, v50
	v_mov_b32_e32 v52, v50
	v_mov_b32_e32 v53, v50
	v_mov_b32_e32 v54, v50
	v_mov_b32_e32 v55, v50
	v_mov_b32_e32 v56, v50
	v_mov_b32_e32 v57, v50
	v_mov_b32_e32 v58, v50
	v_mov_b32_e32 v59, v50
	v_mov_b32_e32 v60, v50
	v_mov_b32_e32 v61, v50
	v_mov_b32_e32 v62, v50
	v_mov_b32_e32 v63, v50
	v_mov_b32_e32 v64, v50
	v_mov_b32_e32 v65, v50
	v_mov_b32_e32 v82, v50
	v_mov_b32_e32 v83, v50
	v_mov_b32_e32 v84, v50
	v_mov_b32_e32 v85, v50
	v_mov_b32_e32 v86, v50
	v_mov_b32_e32 v87, v50
	v_mov_b32_e32 v88, v50
	v_mov_b32_e32 v89, v50
	v_mov_b32_e32 v90, v50
	v_mov_b32_e32 v91, v50
	v_mov_b32_e32 v92, v50
	v_mov_b32_e32 v93, v50
	v_mov_b32_e32 v94, v50
	v_mov_b32_e32 v95, v50
	v_mov_b32_e32 v96, v50
	v_mov_b32_e32 v97, v50
	v_mov_b32_e32 v98, v50
	v_mov_b32_e32 v99, v50
	v_mov_b32_e32 v100, v50
	v_mov_b32_e32 v101, v50
	v_mov_b32_e32 v102, v50
	v_mov_b32_e32 v103, v50
	v_mov_b32_e32 v104, v50
	v_mov_b32_e32 v105, v50
	v_mov_b32_e32 v106, v50
	v_mov_b32_e32 v107, v50
	v_mov_b32_e32 v108, v50
	v_mov_b32_e32 v109, v50
	v_mov_b32_e32 v110, v50
	v_mov_b32_e32 v111, v50
	v_mov_b32_e32 v112, v50
	v_mov_b32_e32 v113, v50
	v_mov_b32_e32 v114, v50
	v_mov_b32_e32 v115, v50
	v_mov_b32_e32 v116, v50
	v_mov_b32_e32 v117, v50
	v_mov_b32_e32 v118, v50
	v_mov_b32_e32 v119, v50
	v_mov_b32_e32 v120, v50
	v_mov_b32_e32 v121, v50
	v_mov_b32_e32 v122, v50
	v_mov_b32_e32 v123, v50
	v_mov_b32_e32 v124, v50
	v_mov_b32_e32 v125, v50
	v_mov_b32_e32 v126, v50
	v_mov_b32_e32 v127, v50
	v_mov_b32_e32 v128, v50
	v_mov_b32_e32 v129, v50
	v_readfirstlane_b32 s56, v162
	v_readfirstlane_b32 s57, v163
	v_readfirstlane_b32 s58, v164
	v_readfirstlane_b32 s59, v165
	v_readfirstlane_b32 s94, v195
	s_nop 3
	s_lshr_b32 s94, s94, 6
	s_mul_i32 s95, s94, 0x2000
	s_sub_u32 s56, s56, s95
	s_subb_u32 s57, s57, 0
	s_sub_u32 s58, s58, s95
	s_subb_u32 s59, s59, 0
	s_lshl_b32 s96, s94, 12
	v_and_b32_e32 v217, 63, v195
	v_lshrrev_b32_e32 v218, 3, v217
	v_lshrrev_b32_e32 v219, 4, v217
	v_and_b32_e32 v222, 7, v217
	v_xor_b32_e32 v219, v219, v222
	v_lshlrev_b32_e32 v219, 4, v219
	v_lshrrev_b32_e32 v222, 6, v195
	v_lshl_add_u32 v217, v222, 5, v218
	v_mul_u32_u24_e32 v217, 0x400, v217
	v_add_u32_e32 v205, v217, v219
	v_xor_b32_e32 v219, 64, v219
	v_add_u32_e32 v217, v217, v219
	v_add_u32_e32 v206, 0x1c00, v217
	v_add_u32_e32 v207, 0x3800, v205
	v_add_u32_e32 v208, 0x5400, v217
	v_and_b32_e32 v217, 31, v195
	v_bfe_u32 v218, v195, 5, 1
	v_bfe_u32 v219, v217, 1, 3
	v_xor_b32_e32 v218, v218, v219
	v_lshlrev_b32_e32 v218, 4, v218
	v_lshrrev_b32_e32 v219, 7, v195
	v_lshl_add_u32 v219, v219, 6, v217
	v_lshl_add_u32 v209, v219, 7, v218
	v_xor_b32_e32 v210, 32, v209
	v_xor_b32_e32 v211, 64, v209
	v_xor_b32_e32 v212, 96, v209
	v_bfe_u32 v219, v195, 6, 1
	v_lshl_add_u32 v219, v219, 6, v217
	v_lshl_add_u32 v213, v219, 7, v218
	v_add_u32_e32 v213, 16384, v213
	v_xor_b32_e32 v214, 32, v213
	v_xor_b32_e32 v215, 64, v213
	v_xor_b32_e32 v216, 96, v213
	s_barrier
	s_add_u32 m0, s96, 0
	s_nop 0
	global_load_lds_dwordx4 v205, s[56:57] offset:0
	global_load_lds_dwordx4 v206, s[56:57] offset:1024
	global_load_lds_dwordx4 v207, s[56:57] offset:2048
	global_load_lds_dwordx4 v208, s[56:57] offset:3072
	s_add_u32 m0, s96, 16384
	s_nop 0
	global_load_lds_dwordx4 v205, s[58:59] offset:0
	global_load_lds_dwordx4 v206, s[58:59] offset:1024
	global_load_lds_dwordx4 v207, s[58:59] offset:2048
	global_load_lds_dwordx4 v208, s[58:59] offset:3072
	s_add_u32 s56, s56, 128
	s_addc_u32 s57, s57, 0
	s_add_u32 s58, s58, 128
	s_addc_u32 s59, s59, 0
	s_waitcnt vmcnt(0)
	s_barrier
; #define MFMA(a, b, c) __builtin_amdgcn_mfma_f32_32x32x16_bf16((a), (b), (c), 0, 0, 0)
; __device__ __forceinline__ unsigned pack2(float a, float b) { f2_t f = {a, b}; return __builtin_bit_cast(unsigned, __builtin_convertvector(f, bf2_t)); }
; __device__ __forceinline__ float sigmoidf_(float x) { return __builtin_amdgcn_rcpf(1.f + fexp(-x)); }
; template <int MI, int NI>
; __device__ __forceinline__ void gemm_kloop(const bf16* __restrict__ A, size_t lda, const bf16* __restrict__ Bt, size_t ldb, int K,
;                                            f16v (&acc)[MI][NI], bf16* sA, bf16* sB) {
;     ...
;   for (int kt = 0; kt < KT; ++kt) {
;     __syncthreads();
; #pragma unroll
;     for (int i = 0; i < 2 * MI; ++i) *(u4v*)(sA + (lrow + 32 * i) * 72 + lseg * 8) = ra[i];
; #pragma unroll
;     for (int i = 0; i < 2 * NI; ++i) *(u4v*)(sB + (lrow + 32 * i) * 72 + lseg * 8) = rb[i];
;     __syncthreads();
;     if (kt + 3 < KT) {
;       const int k2 = (kt + 3) << 6;
;       if (tid < 64 * MI) pfs ^= *(const unsigned*)(A + (size_t)tid * lda + k2);
;       if (tid < 64 * NI) pfs ^= *(const unsigned*)(Bt + (size_t)tid * ldb + k2);
;     }
;     if (kt + 1 < KT) {
;       const int k0 = (kt + 1) << 6;
; #pragma unroll
;       for (int i = 0; i < 2 * MI; ++i) ra[i] = *(const u4v*)(A + (size_t)(lrow + 32 * i) * lda + k0 + lseg * 8);
; #pragma unroll
;       for (int i = 0; i < 2 * NI; ++i) rb[i] = *(const u4v*)(Bt + (size_t)(lrow + 32 * i) * ldb + k0 + lseg * 8);
;     }
; #pragma unroll
;     for (int ks = 0; ks < 4; ++ks) {
;       s8v a[MI], b[NI];
; #pragma unroll
;       for (int mi = 0; mi < MI; ++mi) a[mi] = *(const s8v*)(sA + (wm * 32 * MI + mi * 32 + r) * 72 + ks * 16 + hh * 8);
; #pragma unroll
;       for (int ni = 0; ni < NI; ++ni) b[ni] = *(const s8v*)(sB + (wn * 32 * NI + ni * 32 + r) * 72 + ks * 16 + hh * 8);
; #pragma unroll
;       for (int mi = 0; mi < MI; ++mi)
; #pragma unroll
;         for (int ni = 0; ni < NI; ++ni) acc[mi][ni] = MFMA(a[mi], b[ni], acc[mi][ni]);
;     }
; __device__ __forceinline__ void merge_tile(const Params& p, int mt, int nt, bf16* sA, bf16* sB) {
;     ...
;       for (int mi = 0; mi < 2; ++mi)
; #pragma unroll
;         for (int ni = 0; ni < 2; ++ni)
; #pragma unroll
;           for (int e = 0; e < 8; ++e) sg[mi][ni][e] = pack2(sigmoidf_(ag[mi][ni][2 * e]), sigmoidf_(ag[mi][ni][2 * e + 1]));
	s_add_u32 m0, s96, 32768
	s_nop 0
	global_load_lds_dwordx4 v205, s[56:57] offset:0
	global_load_lds_dwordx4 v206, s[56:57] offset:1024
	global_load_lds_dwordx4 v207, s[56:57] offset:2048
	global_load_lds_dwordx4 v208, s[56:57] offset:3072
	s_add_u32 m0, s96, 49152
	s_nop 0
	global_load_lds_dwordx4 v205, s[58:59] offset:0
	global_load_lds_dwordx4 v206, s[58:59] offset:1024
	global_load_lds_dwordx4 v207, s[58:59] offset:2048
	global_load_lds_dwordx4 v208, s[58:59] offset:3072
	s_add_u32 s56, s56, 128
	s_addc_u32 s57, s57, 0
	s_add_u32 s58, s58, 128
	s_addc_u32 s59, s59, 0
	ds_read_b128 v[130:133], v209 offset:0
	ds_read_b128 v[138:141], v213 offset:0
	ds_read_b128 v[142:145], v213 offset:4096
	ds_read_b128 v[134:137], v209 offset:4096
	ds_read_b128 v[146:149], v210 offset:0
	ds_read_b128 v[154:157], v214 offset:0
	ds_read_b128 v[158:161], v214 offset:4096
	ds_read_b128 v[150:153], v210 offset:4096
	s_waitcnt lgkmcnt(6)
	v_mfma_f32_32x32x16_bf16 v[114:129], v[130:133], v[138:141], v[114:129]
	v_mul_f32_e32 v36, 0xbfb8aa3b, v36
	v_mul_f32_e32 v37, 0xbfb8aa3b, v37
	s_waitcnt lgkmcnt(5)
	v_mfma_f32_32x32x16_bf16 v[98:113], v[130:133], v[142:145], v[98:113]
	v_mul_f32_e32 v66, 0xbfb8aa3b, v66
	v_mul_f32_e32 v67, 0xbfb8aa3b, v67
	s_waitcnt lgkmcnt(4)
	v_mfma_f32_32x32x16_bf16 v[82:97], v[134:137], v[138:141], v[82:97]
	v_exp_f32_e32 v36, v36
	v_exp_f32_e32 v37, v37
	v_mfma_f32_32x32x16_bf16 v[50:65], v[134:137], v[142:145], v[50:65]
	v_exp_f32_e32 v66, v66
	v_exp_f32_e32 v67, v67
	ds_read_b128 v[130:133], v211 offset:0
	ds_read_b128 v[138:141], v215 offset:0
	ds_read_b128 v[142:145], v215 offset:4096
	ds_read_b128 v[134:137], v211 offset:4096
	s_waitcnt lgkmcnt(6)
	v_mfma_f32_32x32x16_bf16 v[114:129], v[146:149], v[154:157], v[114:129]
	v_add_f32_e32 v36, 1.0, v36
	v_add_f32_e32 v37, 1.0, v37
	s_waitcnt lgkmcnt(5)
	v_mfma_f32_32x32x16_bf16 v[98:113], v[146:149], v[158:161], v[98:113]
	v_mul_f32_e32 v38, 0xbfb8aa3b, v38
	v_mul_f32_e32 v39, 0xbfb8aa3b, v39
	s_waitcnt lgkmcnt(4)
	v_mfma_f32_32x32x16_bf16 v[82:97], v[150:153], v[154:157], v[82:97]
	v_add_f32_e32 v66, 1.0, v66
	v_add_f32_e32 v67, 1.0, v67
	v_mfma_f32_32x32x16_bf16 v[50:65], v[150:153], v[158:161], v[50:65]
	v_mul_f32_e32 v68, 0xbfb8aa3b, v68
	v_mul_f32_e32 v69, 0xbfb8aa3b, v69
	ds_read_b128 v[146:149], v212 offset:0
	ds_read_b128 v[154:157], v216 offset:0
	ds_read_b128 v[158:161], v216 offset:4096
	ds_read_b128 v[150:153], v212 offset:4096
	s_waitcnt lgkmcnt(6)
	v_mfma_f32_32x32x16_bf16 v[114:129], v[130:133], v[138:141], v[114:129]
	v_rcp_f32_e32 v36, v36
	v_rcp_f32_e32 v37, v37
	s_waitcnt lgkmcnt(5)
	v_mfma_f32_32x32x16_bf16 v[98:113], v[130:133], v[142:145], v[98:113]
	v_exp_f32_e32 v38, v38
	v_exp_f32_e32 v39, v39
	s_waitcnt lgkmcnt(4)
	v_mfma_f32_32x32x16_bf16 v[82:97], v[134:137], v[138:141], v[82:97]
	v_rcp_f32_e32 v66, v66
	v_rcp_f32_e32 v67, v67
	v_mfma_f32_32x32x16_bf16 v[50:65], v[134:137], v[142:145], v[50:65]
	v_exp_f32_e32 v68, v68
	v_exp_f32_e32 v69, v69
	s_waitcnt lgkmcnt(2)
	v_mfma_f32_32x32x16_bf16 v[114:129], v[146:149], v[154:157], v[114:129]
	v_cvt_pk_bf16_f32 v36, v36, v37
	v_add_f32_e32 v37, 1.0, v38
	s_waitcnt lgkmcnt(1)
	v_mfma_f32_32x32x16_bf16 v[98:113], v[146:149], v[158:161], v[98:113]
	v_add_f32_e32 v38, 1.0, v39
	v_mul_f32_e32 v39, 0xbfb8aa3b, v40
	s_waitcnt lgkmcnt(0)
	v_mfma_f32_32x32x16_bf16 v[82:97], v[150:153], v[154:157], v[82:97]
	v_mul_f32_e32 v40, 0xbfb8aa3b, v41
	v_cvt_pk_bf16_f32 v66, v66, v67
	v_mfma_f32_32x32x16_bf16 v[50:65], v[150:153], v[158:161], v[50:65]
	v_add_f32_e32 v67, 1.0, v68
	v_add_f32_e32 v68, 1.0, v69
	s_waitcnt vmcnt(0)
	s_barrier
	s_add_u32 m0, s96, 0
	s_nop 0
	global_load_lds_dwordx4 v205, s[56:57] offset:0
	global_load_lds_dwordx4 v206, s[56:57] offset:1024
	global_load_lds_dwordx4 v207, s[56:57] offset:2048
	global_load_lds_dwordx4 v208, s[56:57] offset:3072
	s_add_u32 m0, s96, 16384
	s_nop 0
	global_load_lds_dwordx4 v205, s[58:59] offset:0
	global_load_lds_dwordx4 v206, s[58:59] offset:1024
	global_load_lds_dwordx4 v207, s[58:59] offset:2048
	global_load_lds_dwordx4 v208, s[58:59] offset:3072
	s_add_u32 s56, s56, 128
	s_addc_u32 s57, s57, 0
	s_add_u32 s58, s58, 128
	s_addc_u32 s59, s59, 0
	ds_read_b128 v[130:133], v209 offset:32768
	ds_read_b128 v[138:141], v213 offset:32768
	ds_read_b128 v[142:145], v213 offset:36864
	ds_read_b128 v[134:137], v209 offset:36864
	ds_read_b128 v[146:149], v210 offset:32768
	ds_read_b128 v[154:157], v214 offset:32768
	ds_read_b128 v[158:161], v214 offset:36864
	ds_read_b128 v[150:153], v210 offset:36864
	s_waitcnt lgkmcnt(6)
	v_mfma_f32_32x32x16_bf16 v[114:129], v[130:133], v[138:141], v[114:129]
	v_mul_f32_e32 v69, 0xbfb8aa3b, v70
	v_mul_f32_e32 v70, 0xbfb8aa3b, v71
	s_waitcnt lgkmcnt(5)
	v_mfma_f32_32x32x16_bf16 v[98:113], v[130:133], v[142:145], v[98:113]
	v_rcp_f32_e32 v37, v37
	v_rcp_f32_e32 v38, v38
	s_waitcnt lgkmcnt(4)
	v_mfma_f32_32x32x16_bf16 v[82:97], v[134:137], v[138:141], v[82:97]
	v_exp_f32_e32 v39, v39
	v_exp_f32_e32 v40, v40
	v_mfma_f32_32x32x16_bf16 v[50:65], v[134:137], v[142:145], v[50:65]
	v_rcp_f32_e32 v67, v67
	v_rcp_f32_e32 v68, v68
	ds_read_b128 v[130:133], v211 offset:32768
	ds_read_b128 v[138:141], v215 offset:32768
	ds_read_b128 v[142:145], v215 offset:36864
	ds_read_b128 v[134:137], v211 offset:36864
	s_waitcnt lgkmcnt(6)
	v_mfma_f32_32x32x16_bf16 v[114:129], v[146:149], v[154:157], v[114:129]
	v_exp_f32_e32 v69, v69
	v_exp_f32_e32 v70, v70
	s_waitcnt lgkmcnt(5)
	v_mfma_f32_32x32x16_bf16 v[98:113], v[146:149], v[158:161], v[98:113]
	v_cvt_pk_bf16_f32 v37, v37, v38
	v_add_f32_e32 v38, 1.0, v39
	s_waitcnt lgkmcnt(4)
; #define MFMA(a, b, c) __builtin_amdgcn_mfma_f32_32x32x16_bf16((a), (b), (c), 0, 0, 0)
; __device__ __forceinline__ unsigned pack2(float a, float b) { f2_t f = {a, b}; return __builtin_bit_cast(unsigned, __builtin_convertvector(f, bf2_t)); }
; __device__ __forceinline__ float sigmoidf_(float x) { return __builtin_amdgcn_rcpf(1.f + fexp(-x)); }
; template <int MI, int NI>
; __device__ __forceinline__ void gemm_kloop(const bf16* __restrict__ A, size_t lda, const bf16* __restrict__ Bt, size_t ldb, int K,
;                                            f16v (&acc)[MI][NI], bf16* sA, bf16* sB) {
;     ...
;   for (int kt = 0; kt < KT; ++kt) {
;     __syncthreads();
; #pragma unroll
;     for (int i = 0; i < 2 * MI; ++i) *(u4v*)(sA + (lrow + 32 * i) * 72 + lseg * 8) = ra[i];
; #pragma unroll
;     for (int i = 0; i < 2 * NI; ++i) *(u4v*)(sB + (lrow + 32 * i) * 72 + lseg * 8) = rb[i];
;     __syncthreads();
;     if (kt + 3 < KT) {
;       const int k2 = (kt + 3) << 6;
;       if (tid < 64 * MI) pfs ^= *(const unsigned*)(A + (size_t)tid * lda + k2);
;       if (tid < 64 * NI) pfs ^= *(const unsigned*)(Bt + (size_t)tid * ldb + k2);
;     }
;     if (kt + 1 < KT) {
;       const int k0 = (kt + 1) << 6;
; #pragma unroll
;       for (int i = 0; i < 2 * MI; ++i) ra[i] = *(const u4v*)(A + (size_t)(lrow + 32 * i) * lda + k0 + lseg * 8);
; #pragma unroll
;       for (int i = 0; i < 2 * NI; ++i) rb[i] = *(const u4v*)(Bt + (size_t)(lrow + 32 * i) * ldb + k0 + lseg * 8);
;     }
; #pragma unroll
;     for (int ks = 0; ks < 4; ++ks) {
;       s8v a[MI], b[NI];
; #pragma unroll
;       for (int mi = 0; mi < MI; ++mi) a[mi] = *(const s8v*)(sA + (wm * 32 * MI + mi * 32 + r) * 72 + ks * 16 + hh * 8);
; #pragma unroll
;       for (int ni = 0; ni < NI; ++ni) b[ni] = *(const s8v*)(sB + (wn * 32 * NI + ni * 32 + r) * 72 + ks * 16 + hh * 8);
; #pragma unroll
;       for (int mi = 0; mi < MI; ++mi)
; #pragma unroll
;         for (int ni = 0; ni < NI; ++ni) acc[mi][ni] = MFMA(a[mi], b[ni], acc[mi][ni]);
;     }
; __device__ __forceinline__ void merge_tile(const Params& p, int mt, int nt, bf16* sA, bf16* sB) {
;     ...
;       for (int mi = 0; mi < 2; ++mi)
; #pragma unroll
;         for (int ni = 0; ni < 2; ++ni)
; #pragma unroll
;           for (int e = 0; e < 8; ++e) sg[mi][ni][e] = pack2(sigmoidf_(ag[mi][ni][2 * e]), sigmoidf_(ag[mi][ni][2 * e + 1]));
	v_mfma_f32_32x32x16_bf16 v[82:97], v[150:153], v[154:157], v[82:97]
	v_add_f32_e32 v39, 1.0, v40
	v_mul_f32_e32 v40, 0xbfb8aa3b, v42
	v_mfma_f32_32x32x16_bf16 v[50:65], v[150:153], v[158:161], v[50:65]
	v_mul_f32_e32 v41, 0xbfb8aa3b, v43
	v_cvt_pk_bf16_f32 v67, v67, v68
	ds_read_b128 v[146:149], v212 offset:32768
	ds_read_b128 v[154:157], v216 offset:32768
	ds_read_b128 v[158:161], v216 offset:36864
	ds_read_b128 v[150:153], v212 offset:36864
	s_waitcnt lgkmcnt(6)
	v_mfma_f32_32x32x16_bf16 v[114:129], v[130:133], v[138:141], v[114:129]
	v_add_f32_e32 v68, 1.0, v69
	v_add_f32_e32 v69, 1.0, v70
	s_waitcnt lgkmcnt(5)
	v_mfma_f32_32x32x16_bf16 v[98:113], v[130:133], v[142:145], v[98:113]
	v_mul_f32_e32 v70, 0xbfb8aa3b, v72
	v_mul_f32_e32 v71, 0xbfb8aa3b, v73
	s_waitcnt lgkmcnt(4)
	v_mfma_f32_32x32x16_bf16 v[82:97], v[134:137], v[138:141], v[82:97]
	v_rcp_f32_e32 v38, v38
	v_rcp_f32_e32 v39, v39
	v_mfma_f32_32x32x16_bf16 v[50:65], v[134:137], v[142:145], v[50:65]
	v_exp_f32_e32 v40, v40
	v_exp_f32_e32 v41, v41
	s_waitcnt lgkmcnt(2)
	v_mfma_f32_32x32x16_bf16 v[114:129], v[146:149], v[154:157], v[114:129]
	v_rcp_f32_e32 v68, v68
	v_rcp_f32_e32 v69, v69
	s_waitcnt lgkmcnt(1)
	v_mfma_f32_32x32x16_bf16 v[98:113], v[146:149], v[158:161], v[98:113]
	v_exp_f32_e32 v70, v70
	v_exp_f32_e32 v71, v71
	s_waitcnt lgkmcnt(0)
	v_mfma_f32_32x32x16_bf16 v[82:97], v[150:153], v[154:157], v[82:97]
	v_cvt_pk_bf16_f32 v38, v38, v39
	v_add_f32_e32 v39, 1.0, v40
	v_mfma_f32_32x32x16_bf16 v[50:65], v[150:153], v[158:161], v[50:65]
	v_add_f32_e32 v40, 1.0, v41
	v_mul_f32_e32 v41, 0xbfb8aa3b, v44
	s_waitcnt vmcnt(0)
	s_barrier
	s_add_u32 m0, s96, 32768
	s_nop 0
	global_load_lds_dwordx4 v205, s[56:57] offset:0
	global_load_lds_dwordx4 v206, s[56:57] offset:1024
	global_load_lds_dwordx4 v207, s[56:57] offset:2048
	global_load_lds_dwordx4 v208, s[56:57] offset:3072
	s_add_u32 m0, s96, 49152
	s_nop 0
	global_load_lds_dwordx4 v205, s[58:59] offset:0
	global_load_lds_dwordx4 v206, s[58:59] offset:1024
	global_load_lds_dwordx4 v207, s[58:59] offset:2048
	global_load_lds_dwordx4 v208, s[58:59] offset:3072
	s_add_u32 s56, s56, 128
	s_addc_u32 s57, s57, 0
	s_add_u32 s58, s58, 128
	s_addc_u32 s59, s59, 0
	ds_read_b128 v[130:133], v209 offset:0
	ds_read_b128 v[138:141], v213 offset:0
	ds_read_b128 v[142:145], v213 offset:4096
	ds_read_b128 v[134:137], v209 offset:4096
	ds_read_b128 v[146:149], v210 offset:0
	ds_read_b128 v[154:157], v214 offset:0
	ds_read_b128 v[158:161], v214 offset:4096
	ds_read_b128 v[150:153], v210 offset:4096
	s_waitcnt lgkmcnt(6)
	v_mfma_f32_32x32x16_bf16 v[114:129], v[130:133], v[138:141], v[114:129]
	v_mul_f32_e32 v42, 0xbfb8aa3b, v45
	v_cvt_pk_bf16_f32 v68, v68, v69
	s_waitcnt lgkmcnt(5)
	v_mfma_f32_32x32x16_bf16 v[98:113], v[130:133], v[142:145], v[98:113]
	v_add_f32_e32 v69, 1.0, v70
	v_add_f32_e32 v70, 1.0, v71
	s_waitcnt lgkmcnt(4)
	v_mfma_f32_32x32x16_bf16 v[82:97], v[134:137], v[138:141], v[82:97]
	v_mul_f32_e32 v71, 0xbfb8aa3b, v74
	v_mul_f32_e32 v72, 0xbfb8aa3b, v75
	v_mfma_f32_32x32x16_bf16 v[50:65], v[134:137], v[142:145], v[50:65]
	v_rcp_f32_e32 v39, v39
	v_rcp_f32_e32 v40, v40
	ds_read_b128 v[130:133], v211 offset:0
	ds_read_b128 v[138:141], v215 offset:0
	ds_read_b128 v[142:145], v215 offset:4096
	ds_read_b128 v[134:137], v211 offset:4096
	s_waitcnt lgkmcnt(6)
	v_mfma_f32_32x32x16_bf16 v[114:129], v[146:149], v[154:157], v[114:129]
	v_exp_f32_e32 v41, v41
	v_exp_f32_e32 v42, v42
	s_waitcnt lgkmcnt(5)
	v_mfma_f32_32x32x16_bf16 v[98:113], v[146:149], v[158:161], v[98:113]
	v_rcp_f32_e32 v69, v69
	v_rcp_f32_e32 v70, v70
	s_waitcnt lgkmcnt(4)
	v_mfma_f32_32x32x16_bf16 v[82:97], v[150:153], v[154:157], v[82:97]
	v_exp_f32_e32 v71, v71
	v_exp_f32_e32 v72, v72
	v_mfma_f32_32x32x16_bf16 v[50:65], v[150:153], v[158:161], v[50:65]
	v_mul_f32_e32 v20, 0xbfb8aa3b, v20
	v_mul_f32_e32 v21, 0xbfb8aa3b, v21
	ds_read_b128 v[146:149], v212 offset:0
	ds_read_b128 v[154:157], v216 offset:0
	ds_read_b128 v[158:161], v216 offset:4096
	ds_read_b128 v[150:153], v212 offset:4096
	s_waitcnt lgkmcnt(6)
	v_mfma_f32_32x32x16_bf16 v[114:129], v[130:133], v[138:141], v[114:129]
	v_cvt_pk_bf16_f32 v39, v39, v40
	v_add_f32_e32 v40, 1.0, v41
	s_waitcnt lgkmcnt(5)
	v_mfma_f32_32x32x16_bf16 v[98:113], v[130:133], v[142:145], v[98:113]
	v_add_f32_e32 v41, 1.0, v42
	v_mul_f32_e32 v42, 0xbfb8aa3b, v46
	s_waitcnt lgkmcnt(4)
	v_mfma_f32_32x32x16_bf16 v[82:97], v[134:137], v[138:141], v[82:97]
	v_mul_f32_e32 v43, 0xbfb8aa3b, v47
	v_exp_f32_e32 v20, v20
	v_mfma_f32_32x32x16_bf16 v[50:65], v[134:137], v[142:145], v[50:65]
	v_exp_f32_e32 v21, v21
	v_cvt_pk_bf16_f32 v69, v69, v70
	s_waitcnt lgkmcnt(2)
	v_mfma_f32_32x32x16_bf16 v[114:129], v[146:149], v[154:157], v[114:129]
	v_add_f32_e32 v70, 1.0, v71
	v_add_f32_e32 v71, 1.0, v72
	s_waitcnt lgkmcnt(1)
	v_mfma_f32_32x32x16_bf16 v[98:113], v[146:149], v[158:161], v[98:113]
	v_mul_f32_e32 v72, 0xbfb8aa3b, v76
	v_mul_f32_e32 v73, 0xbfb8aa3b, v77
	s_waitcnt lgkmcnt(0)
	v_mfma_f32_32x32x16_bf16 v[82:97], v[150:153], v[154:157], v[82:97]
	v_rcp_f32_e32 v40, v40
	v_rcp_f32_e32 v41, v41
	v_mfma_f32_32x32x16_bf16 v[50:65], v[150:153], v[158:161], v[50:65]
	v_exp_f32_e32 v42, v42
	v_exp_f32_e32 v43, v43
	s_waitcnt vmcnt(0)
	s_barrier
; #define MFMA(a, b, c) __builtin_amdgcn_mfma_f32_32x32x16_bf16((a), (b), (c), 0, 0, 0)
; __device__ __forceinline__ unsigned pack2(float a, float b) { f2_t f = {a, b}; return __builtin_bit_cast(unsigned, __builtin_convertvector(f, bf2_t)); }
; __device__ __forceinline__ float sigmoidf_(float x) { return __builtin_amdgcn_rcpf(1.f + fexp(-x)); }
; template <int MI, int NI>
; __device__ __forceinline__ void gemm_kloop(const bf16* __restrict__ A, size_t lda, const bf16* __restrict__ Bt, size_t ldb, int K,
;                                            f16v (&acc)[MI][NI], bf16* sA, bf16* sB) {
;     ...
;   for (int kt = 0; kt < KT; ++kt) {
;     __syncthreads();
; #pragma unroll
;     for (int i = 0; i < 2 * MI; ++i) *(u4v*)(sA + (lrow + 32 * i) * 72 + lseg * 8) = ra[i];
; #pragma unroll
;     for (int i = 0; i < 2 * NI; ++i) *(u4v*)(sB + (lrow + 32 * i) * 72 + lseg * 8) = rb[i];
;     __syncthreads();
;     if (kt + 3 < KT) {
;       const int k2 = (kt + 3) << 6;
;       if (tid < 64 * MI) pfs ^= *(const unsigned*)(A + (size_t)tid * lda + k2);
;       if (tid < 64 * NI) pfs ^= *(const unsigned*)(Bt + (size_t)tid * ldb + k2);
;     }
;     if (kt + 1 < KT) {
;       const int k0 = (kt + 1) << 6;
; #pragma unroll
;       for (int i = 0; i < 2 * MI; ++i) ra[i] = *(const u4v*)(A + (size_t)(lrow + 32 * i) * lda + k0 + lseg * 8);
; #pragma unroll
;       for (int i = 0; i < 2 * NI; ++i) rb[i] = *(const u4v*)(Bt + (size_t)(lrow + 32 * i) * ldb + k0 + lseg * 8);
;     }
; #pragma unroll
;     for (int ks = 0; ks < 4; ++ks) {
;       s8v a[MI], b[NI];
; #pragma unroll
;       for (int mi = 0; mi < MI; ++mi) a[mi] = *(const s8v*)(sA + (wm * 32 * MI + mi * 32 + r) * 72 + ks * 16 + hh * 8);
; #pragma unroll
;       for (int ni = 0; ni < NI; ++ni) b[ni] = *(const s8v*)(sB + (wn * 32 * NI + ni * 32 + r) * 72 + ks * 16 + hh * 8);
; #pragma unroll
;       for (int mi = 0; mi < MI; ++mi)
; #pragma unroll
;         for (int ni = 0; ni < NI; ++ni) acc[mi][ni] = MFMA(a[mi], b[ni], acc[mi][ni]);
;     }
; __device__ __forceinline__ void merge_tile(const Params& p, int mt, int nt, bf16* sA, bf16* sB) {
;     ...
;       for (int mi = 0; mi < 2; ++mi)
; #pragma unroll
;         for (int ni = 0; ni < 2; ++ni)
; #pragma unroll
;           for (int e = 0; e < 8; ++e) sg[mi][ni][e] = pack2(sigmoidf_(ag[mi][ni][2 * e]), sigmoidf_(ag[mi][ni][2 * e + 1]));
	s_add_u32 m0, s96, 0
	s_nop 0
	global_load_lds_dwordx4 v205, s[56:57] offset:0
	global_load_lds_dwordx4 v206, s[56:57] offset:1024
	global_load_lds_dwordx4 v207, s[56:57] offset:2048
	global_load_lds_dwordx4 v208, s[56:57] offset:3072
	s_add_u32 m0, s96, 16384
	s_nop 0
	global_load_lds_dwordx4 v205, s[58:59] offset:0
	global_load_lds_dwordx4 v206, s[58:59] offset:1024
	global_load_lds_dwordx4 v207, s[58:59] offset:2048
	global_load_lds_dwordx4 v208, s[58:59] offset:3072
	s_add_u32 s56, s56, 128
	s_addc_u32 s57, s57, 0
	s_add_u32 s58, s58, 128
	s_addc_u32 s59, s59, 0
	ds_read_b128 v[130:133], v209 offset:32768
	ds_read_b128 v[138:141], v213 offset:32768
	ds_read_b128 v[142:145], v213 offset:36864
	ds_read_b128 v[134:137], v209 offset:36864
	ds_read_b128 v[146:149], v210 offset:32768
	ds_read_b128 v[154:157], v214 offset:32768
	ds_read_b128 v[158:161], v214 offset:36864
	ds_read_b128 v[150:153], v210 offset:36864
	s_waitcnt lgkmcnt(6)
	v_mfma_f32_32x32x16_bf16 v[114:129], v[130:133], v[138:141], v[114:129]
	v_rcp_f32_e32 v70, v70
	v_rcp_f32_e32 v71, v71
	s_waitcnt lgkmcnt(5)
	v_mfma_f32_32x32x16_bf16 v[98:113], v[130:133], v[142:145], v[98:113]
	v_exp_f32_e32 v72, v72
	v_exp_f32_e32 v73, v73
	s_waitcnt lgkmcnt(4)
	v_mfma_f32_32x32x16_bf16 v[82:97], v[134:137], v[138:141], v[82:97]
	v_add_f32_e32 v20, 1.0, v20
	v_add_f32_e32 v21, 1.0, v21
	v_mfma_f32_32x32x16_bf16 v[50:65], v[134:137], v[142:145], v[50:65]
	v_mul_f32_e32 v22, 0xbfb8aa3b, v22
	v_mul_f32_e32 v23, 0xbfb8aa3b, v23
	ds_read_b128 v[130:133], v211 offset:32768
	ds_read_b128 v[138:141], v215 offset:32768
	ds_read_b128 v[142:145], v215 offset:36864
	ds_read_b128 v[134:137], v211 offset:36864
	s_waitcnt lgkmcnt(6)
	v_mfma_f32_32x32x16_bf16 v[114:129], v[146:149], v[154:157], v[114:129]
	v_cvt_pk_bf16_f32 v40, v40, v41
	v_add_f32_e32 v41, 1.0, v42
	s_waitcnt lgkmcnt(5)
	v_mfma_f32_32x32x16_bf16 v[98:113], v[146:149], v[158:161], v[98:113]
	v_add_f32_e32 v42, 1.0, v43
	v_mul_f32_e32 v43, 0xbfb8aa3b, v48
	s_waitcnt lgkmcnt(4)
	v_mfma_f32_32x32x16_bf16 v[82:97], v[150:153], v[154:157], v[82:97]
	v_mul_f32_e32 v44, 0xbfb8aa3b, v49
	v_rcp_f32_e32 v20, v20
	v_mfma_f32_32x32x16_bf16 v[50:65], v[150:153], v[158:161], v[50:65]
	v_rcp_f32_e32 v21, v21
	v_exp_f32_e32 v22, v22
	ds_read_b128 v[146:149], v212 offset:32768
	ds_read_b128 v[154:157], v216 offset:32768
	ds_read_b128 v[158:161], v216 offset:36864
	ds_read_b128 v[150:153], v212 offset:36864
	s_waitcnt lgkmcnt(6)
	v_mfma_f32_32x32x16_bf16 v[114:129], v[130:133], v[138:141], v[114:129]
	v_exp_f32_e32 v23, v23
	v_cvt_pk_bf16_f32 v70, v70, v71
	s_waitcnt lgkmcnt(5)
	v_mfma_f32_32x32x16_bf16 v[98:113], v[130:133], v[142:145], v[98:113]
	v_add_f32_e32 v71, 1.0, v72
	v_add_f32_e32 v72, 1.0, v73
	s_waitcnt lgkmcnt(4)
	v_mfma_f32_32x32x16_bf16 v[82:97], v[134:137], v[138:141], v[82:97]
	v_mul_f32_e32 v73, 0xbfb8aa3b, v78
	v_mul_f32_e32 v74, 0xbfb8aa3b, v79
	v_mfma_f32_32x32x16_bf16 v[50:65], v[134:137], v[142:145], v[50:65]
	v_rcp_f32_e32 v41, v41
	v_rcp_f32_e32 v42, v42
	s_waitcnt lgkmcnt(2)
	v_mfma_f32_32x32x16_bf16 v[114:129], v[146:149], v[154:157], v[114:129]
	v_exp_f32_e32 v43, v43
	v_exp_f32_e32 v44, v44
	s_waitcnt lgkmcnt(1)
	v_mfma_f32_32x32x16_bf16 v[98:113], v[146:149], v[158:161], v[98:113]
	v_rcp_f32_e32 v71, v71
	v_rcp_f32_e32 v72, v72
	s_waitcnt lgkmcnt(0)
	v_mfma_f32_32x32x16_bf16 v[82:97], v[150:153], v[154:157], v[82:97]
	v_exp_f32_e32 v73, v73
	v_exp_f32_e32 v74, v74
	v_mfma_f32_32x32x16_bf16 v[50:65], v[150:153], v[158:161], v[50:65]
	v_mul_f32_e32 v18, 0xbfb8aa3b, v18
	v_cvt_pk_bf16_f32 v20, v20, v21
	s_waitcnt vmcnt(0)
	s_barrier
	s_add_u32 m0, s96, 32768
	s_nop 0
	global_load_lds_dwordx4 v205, s[56:57] offset:0
	global_load_lds_dwordx4 v206, s[56:57] offset:1024
	global_load_lds_dwordx4 v207, s[56:57] offset:2048
	global_load_lds_dwordx4 v208, s[56:57] offset:3072
	s_add_u32 m0, s96, 49152
	s_nop 0
	global_load_lds_dwordx4 v205, s[58:59] offset:0
	global_load_lds_dwordx4 v206, s[58:59] offset:1024
	global_load_lds_dwordx4 v207, s[58:59] offset:2048
	global_load_lds_dwordx4 v208, s[58:59] offset:3072
	s_add_u32 s56, s56, 128
	s_addc_u32 s57, s57, 0
	s_add_u32 s58, s58, 128
	s_addc_u32 s59, s59, 0
	ds_read_b128 v[130:133], v209 offset:0
	ds_read_b128 v[138:141], v213 offset:0
	ds_read_b128 v[142:145], v213 offset:4096
	ds_read_b128 v[134:137], v209 offset:4096
	ds_read_b128 v[146:149], v210 offset:0
	ds_read_b128 v[154:157], v214 offset:0
	ds_read_b128 v[158:161], v214 offset:4096
	ds_read_b128 v[150:153], v210 offset:4096
	s_waitcnt lgkmcnt(6)
	v_mfma_f32_32x32x16_bf16 v[114:129], v[130:133], v[138:141], v[114:129]
	v_add_f32_e32 v21, 1.0, v22
	v_add_f32_e32 v22, 1.0, v23
	s_waitcnt lgkmcnt(5)
	v_mfma_f32_32x32x16_bf16 v[98:113], v[130:133], v[142:145], v[98:113]
	v_mul_f32_e32 v23, 0xbfb8aa3b, v24
	v_mul_f32_e32 v24, 0xbfb8aa3b, v25
	s_waitcnt lgkmcnt(4)
	v_mfma_f32_32x32x16_bf16 v[82:97], v[134:137], v[138:141], v[82:97]
	v_cvt_pk_bf16_f32 v41, v41, v42
	v_add_f32_e32 v42, 1.0, v43
	v_mfma_f32_32x32x16_bf16 v[50:65], v[134:137], v[142:145], v[50:65]
	v_add_f32_e32 v43, 1.0, v44
	v_exp_f32_e32 v44, v18
	ds_read_b128 v[130:133], v211 offset:0
	ds_read_b128 v[138:141], v215 offset:0
	ds_read_b128 v[142:145], v215 offset:4096
	ds_read_b128 v[134:137], v211 offset:4096
	s_waitcnt lgkmcnt(6)
	v_mfma_f32_32x32x16_bf16 v[114:129], v[146:149], v[154:157], v[114:129]
	v_mul_f32_e32 v18, 0xbfb8aa3b, v19
	v_rcp_f32_e32 v21, v21
	s_waitcnt lgkmcnt(5)
	v_mfma_f32_32x32x16_bf16 v[98:113], v[146:149], v[158:161], v[98:113]
	v_rcp_f32_e32 v22, v22
	v_exp_f32_e32 v23, v23
	s_waitcnt lgkmcnt(4)
; #define MFMA(a, b, c) __builtin_amdgcn_mfma_f32_32x32x16_bf16((a), (b), (c), 0, 0, 0)
; __device__ __forceinline__ unsigned pack2(float a, float b) { f2_t f = {a, b}; return __builtin_bit_cast(unsigned, __builtin_convertvector(f, bf2_t)); }
; __device__ __forceinline__ float sigmoidf_(float x) { return __builtin_amdgcn_rcpf(1.f + fexp(-x)); }
; template <int MI, int NI>
; __device__ __forceinline__ void gemm_kloop(const bf16* __restrict__ A, size_t lda, const bf16* __restrict__ Bt, size_t ldb, int K,
;                                            f16v (&acc)[MI][NI], bf16* sA, bf16* sB) {
;     ...
;   for (int kt = 0; kt < KT; ++kt) {
;     __syncthreads();
; #pragma unroll
;     for (int i = 0; i < 2 * MI; ++i) *(u4v*)(sA + (lrow + 32 * i) * 72 + lseg * 8) = ra[i];
; #pragma unroll
;     for (int i = 0; i < 2 * NI; ++i) *(u4v*)(sB + (lrow + 32 * i) * 72 + lseg * 8) = rb[i];
;     __syncthreads();
;     if (kt + 3 < KT) {
;       const int k2 = (kt + 3) << 6;
;       if (tid < 64 * MI) pfs ^= *(const unsigned*)(A + (size_t)tid * lda + k2);
;       if (tid < 64 * NI) pfs ^= *(const unsigned*)(Bt + (size_t)tid * ldb + k2);
;     }
;     if (kt + 1 < KT) {
;       const int k0 = (kt + 1) << 6;
; #pragma unroll
;       for (int i = 0; i < 2 * MI; ++i) ra[i] = *(const u4v*)(A + (size_t)(lrow + 32 * i) * lda + k0 + lseg * 8);
; #pragma unroll
;       for (int i = 0; i < 2 * NI; ++i) rb[i] = *(const u4v*)(Bt + (size_t)(lrow + 32 * i) * ldb + k0 + lseg * 8);
;     }
; #pragma unroll
;     for (int ks = 0; ks < 4; ++ks) {
;       s8v a[MI], b[NI];
; #pragma unroll
;       for (int mi = 0; mi < MI; ++mi) a[mi] = *(const s8v*)(sA + (wm * 32 * MI + mi * 32 + r) * 72 + ks * 16 + hh * 8);
; #pragma unroll
;       for (int ni = 0; ni < NI; ++ni) b[ni] = *(const s8v*)(sB + (wn * 32 * NI + ni * 32 + r) * 72 + ks * 16 + hh * 8);
; #pragma unroll
;       for (int mi = 0; mi < MI; ++mi)
; #pragma unroll
;         for (int ni = 0; ni < NI; ++ni) acc[mi][ni] = MFMA(a[mi], b[ni], acc[mi][ni]);
;     }
; __device__ __forceinline__ void merge_tile(const Params& p, int mt, int nt, bf16* sA, bf16* sB) {
;     ...
;       for (int mi = 0; mi < 2; ++mi)
; #pragma unroll
;         for (int ni = 0; ni < 2; ++ni)
; #pragma unroll
;           for (int e = 0; e < 8; ++e) sg[mi][ni][e] = pack2(sigmoidf_(ag[mi][ni][2 * e]), sigmoidf_(ag[mi][ni][2 * e + 1]));
	v_mfma_f32_32x32x16_bf16 v[82:97], v[150:153], v[154:157], v[82:97]
	v_exp_f32_e32 v24, v24
	v_cvt_pk_bf16_f32 v71, v71, v72
	v_mfma_f32_32x32x16_bf16 v[50:65], v[150:153], v[158:161], v[50:65]
	v_add_f32_e32 v72, 1.0, v73
	v_add_f32_e32 v73, 1.0, v74
	ds_read_b128 v[146:149], v212 offset:0
	ds_read_b128 v[154:157], v216 offset:0
	ds_read_b128 v[158:161], v216 offset:4096
	ds_read_b128 v[150:153], v212 offset:4096
	s_waitcnt lgkmcnt(6)
	v_mfma_f32_32x32x16_bf16 v[114:129], v[130:133], v[138:141], v[114:129]
	v_mul_f32_e32 v74, 0xbfb8aa3b, v80
	v_mul_f32_e32 v75, 0xbfb8aa3b, v81
	s_waitcnt lgkmcnt(5)
	v_mfma_f32_32x32x16_bf16 v[98:113], v[130:133], v[142:145], v[98:113]
	v_rcp_f32_e32 v42, v42
	v_rcp_f32_e32 v43, v43
	s_waitcnt lgkmcnt(4)
	v_mfma_f32_32x32x16_bf16 v[82:97], v[134:137], v[138:141], v[82:97]
	v_exp_f32_e32 v19, v18
	v_rcp_f32_e32 v72, v72
	v_mfma_f32_32x32x16_bf16 v[50:65], v[134:137], v[142:145], v[50:65]
	v_rcp_f32_e32 v73, v73
	v_exp_f32_e32 v74, v74
	s_waitcnt lgkmcnt(2)
	v_mfma_f32_32x32x16_bf16 v[114:129], v[146:149], v[154:157], v[114:129]
	v_exp_f32_e32 v75, v75
	v_cvt_pk_bf16_f32 v21, v21, v22
	s_waitcnt lgkmcnt(1)
	v_mfma_f32_32x32x16_bf16 v[98:113], v[146:149], v[158:161], v[98:113]
	v_add_f32_e32 v22, 1.0, v23
	v_add_f32_e32 v23, 1.0, v24
	s_waitcnt lgkmcnt(0)
	v_mfma_f32_32x32x16_bf16 v[82:97], v[150:153], v[154:157], v[82:97]
	v_mul_f32_e32 v24, 0xbfb8aa3b, v26
	v_mul_f32_e32 v25, 0xbfb8aa3b, v27
	v_mfma_f32_32x32x16_bf16 v[50:65], v[150:153], v[158:161], v[50:65]
	v_mul_f32_e32 v34, 0xbfb8aa3b, v34
	v_cvt_pk_bf16_f32 v18, v42, v43
	s_waitcnt vmcnt(0)
	s_barrier
	s_add_u32 m0, s96, 0
	s_nop 0
	global_load_lds_dwordx4 v205, s[56:57] offset:0
	global_load_lds_dwordx4 v206, s[56:57] offset:1024
	global_load_lds_dwordx4 v207, s[56:57] offset:2048
	global_load_lds_dwordx4 v208, s[56:57] offset:3072
	s_add_u32 m0, s96, 16384
	s_nop 0
	global_load_lds_dwordx4 v205, s[58:59] offset:0
	global_load_lds_dwordx4 v206, s[58:59] offset:1024
	global_load_lds_dwordx4 v207, s[58:59] offset:2048
	global_load_lds_dwordx4 v208, s[58:59] offset:3072
	s_add_u32 s56, s56, 128
	s_addc_u32 s57, s57, 0
	s_add_u32 s58, s58, 128
	s_addc_u32 s59, s59, 0
	ds_read_b128 v[130:133], v209 offset:32768
	ds_read_b128 v[138:141], v213 offset:32768
	ds_read_b128 v[142:145], v213 offset:36864
	ds_read_b128 v[134:137], v209 offset:36864
	ds_read_b128 v[146:149], v210 offset:32768
	ds_read_b128 v[154:157], v214 offset:32768
	ds_read_b128 v[158:161], v214 offset:36864
	ds_read_b128 v[150:153], v210 offset:36864
	s_waitcnt lgkmcnt(6)
	v_mfma_f32_32x32x16_bf16 v[114:129], v[130:133], v[138:141], v[114:129]
	v_add_f32_e32 v42, 1.0, v44
	v_add_f32_e32 v19, 1.0, v19
	s_waitcnt lgkmcnt(5)
	v_mfma_f32_32x32x16_bf16 v[98:113], v[130:133], v[142:145], v[98:113]
	v_rcp_f32_e32 v22, v22
	v_rcp_f32_e32 v23, v23
	s_waitcnt lgkmcnt(4)
	v_mfma_f32_32x32x16_bf16 v[82:97], v[134:137], v[138:141], v[82:97]
	v_exp_f32_e32 v24, v24
	v_exp_f32_e32 v25, v25
	v_mfma_f32_32x32x16_bf16 v[50:65], v[134:137], v[142:145], v[50:65]
	v_cvt_pk_bf16_f32 v72, v72, v73
	v_add_f32_e32 v73, 1.0, v74
	ds_read_b128 v[130:133], v211 offset:32768
	ds_read_b128 v[138:141], v215 offset:32768
	ds_read_b128 v[142:145], v215 offset:36864
	ds_read_b128 v[134:137], v211 offset:36864
	s_waitcnt lgkmcnt(6)
	v_mfma_f32_32x32x16_bf16 v[114:129], v[146:149], v[154:157], v[114:129]
	v_add_f32_e32 v74, 1.0, v75
	v_exp_f32_e32 v75, v34
	s_waitcnt lgkmcnt(5)
	v_mfma_f32_32x32x16_bf16 v[98:113], v[146:149], v[158:161], v[98:113]
	v_mul_f32_e32 v34, 0xbfb8aa3b, v35
	v_rcp_f32_e32 v42, v42
	s_waitcnt lgkmcnt(4)
	v_mfma_f32_32x32x16_bf16 v[82:97], v[150:153], v[154:157], v[82:97]
	v_rcp_f32_e32 v19, v19
	v_rcp_f32_e32 v73, v73
	v_mfma_f32_32x32x16_bf16 v[50:65], v[150:153], v[158:161], v[50:65]
	v_rcp_f32_e32 v74, v74
	v_exp_f32_e32 v35, v34
	ds_read_b128 v[146:149], v212 offset:32768
	ds_read_b128 v[154:157], v216 offset:32768
	ds_read_b128 v[158:161], v216 offset:36864
	ds_read_b128 v[150:153], v212 offset:36864
	s_waitcnt lgkmcnt(6)
	v_mfma_f32_32x32x16_bf16 v[114:129], v[130:133], v[138:141], v[114:129]
	v_cvt_pk_bf16_f32 v22, v22, v23
	v_add_f32_e32 v23, 1.0, v24
	s_waitcnt lgkmcnt(5)
	v_mfma_f32_32x32x16_bf16 v[98:113], v[130:133], v[142:145], v[98:113]
	v_add_f32_e32 v24, 1.0, v25
	v_cvt_pk_bf16_f32 v19, v42, v19
	s_waitcnt lgkmcnt(4)
	v_mfma_f32_32x32x16_bf16 v[82:97], v[134:137], v[138:141], v[82:97]
	v_rcp_f32_e32 v42, v24
	v_mul_f32_e32 v24, 0xbfb8aa3b, v28
	v_mfma_f32_32x32x16_bf16 v[50:65], v[134:137], v[142:145], v[50:65]
	v_cvt_pk_bf16_f32 v34, v73, v74
	v_add_f32_e32 v73, 1.0, v75
	s_waitcnt lgkmcnt(2)
	v_mfma_f32_32x32x16_bf16 v[114:129], v[146:149], v[154:157], v[114:129]
	v_add_f32_e32 v35, 1.0, v35
	v_exp_f32_e32 v28, v24
	s_waitcnt lgkmcnt(1)
	v_mfma_f32_32x32x16_bf16 v[98:113], v[146:149], v[158:161], v[98:113]
	v_rcp_f32_e32 v73, v73
	v_rcp_f32_e32 v35, v35
	s_waitcnt lgkmcnt(0)
	v_mfma_f32_32x32x16_bf16 v[82:97], v[150:153], v[154:157], v[82:97]
	v_rcp_f32_e32 v23, v23
	v_add_f32_e32 v28, 1.0, v28
	v_mfma_f32_32x32x16_bf16 v[50:65], v[150:153], v[158:161], v[50:65]
	v_cvt_pk_bf16_f32 v35, v73, v35
	v_rcp_f32_e32 v73, v28
	s_waitcnt vmcnt(0)
	s_barrier
; #define MFMA(a, b, c) __builtin_amdgcn_mfma_f32_32x32x16_bf16((a), (b), (c), 0, 0, 0)
; __device__ __forceinline__ unsigned pack2(float a, float b) { f2_t f = {a, b}; return __builtin_bit_cast(unsigned, __builtin_convertvector(f, bf2_t)); }
; __device__ __forceinline__ float sigmoidf_(float x) { return __builtin_amdgcn_rcpf(1.f + fexp(-x)); }
; template <int MI, int NI>
; __device__ __forceinline__ void gemm_kloop(const bf16* __restrict__ A, size_t lda, const bf16* __restrict__ Bt, size_t ldb, int K,
;                                            f16v (&acc)[MI][NI], bf16* sA, bf16* sB) {
;     ...
;   for (int kt = 0; kt < KT; ++kt) {
;     __syncthreads();
; #pragma unroll
;     for (int i = 0; i < 2 * MI; ++i) *(u4v*)(sA + (lrow + 32 * i) * 72 + lseg * 8) = ra[i];
; #pragma unroll
;     for (int i = 0; i < 2 * NI; ++i) *(u4v*)(sB + (lrow + 32 * i) * 72 + lseg * 8) = rb[i];
;     __syncthreads();
;     if (kt + 3 < KT) {
;       const int k2 = (kt + 3) << 6;
;       if (tid < 64 * MI) pfs ^= *(const unsigned*)(A + (size_t)tid * lda + k2);
;       if (tid < 64 * NI) pfs ^= *(const unsigned*)(Bt + (size_t)tid * ldb + k2);
;     }
;     if (kt + 1 < KT) {
;       const int k0 = (kt + 1) << 6;
; #pragma unroll
;       for (int i = 0; i < 2 * MI; ++i) ra[i] = *(const u4v*)(A + (size_t)(lrow + 32 * i) * lda + k0 + lseg * 8);
; #pragma unroll
;       for (int i = 0; i < 2 * NI; ++i) rb[i] = *(const u4v*)(Bt + (size_t)(lrow + 32 * i) * ldb + k0 + lseg * 8);
;     }
; #pragma unroll
;     for (int ks = 0; ks < 4; ++ks) {
;       s8v a[MI], b[NI];
; #pragma unroll
;       for (int mi = 0; mi < MI; ++mi) a[mi] = *(const s8v*)(sA + (wm * 32 * MI + mi * 32 + r) * 72 + ks * 16 + hh * 8);
; #pragma unroll
;       for (int ni = 0; ni < NI; ++ni) b[ni] = *(const s8v*)(sB + (wn * 32 * NI + ni * 32 + r) * 72 + ks * 16 + hh * 8);
; #pragma unroll
;       for (int mi = 0; mi < MI; ++mi)
; #pragma unroll
;         for (int ni = 0; ni < NI; ++ni) acc[mi][ni] = MFMA(a[mi], b[ni], acc[mi][ni]);
;     }
; __device__ __forceinline__ void merge_tile(const Params& p, int mt, int nt, bf16* sA, bf16* sB) {
;     ...
;       for (int mi = 0; mi < 2; ++mi)
; #pragma unroll
;         for (int ni = 0; ni < 2; ++ni)
; #pragma unroll
;           for (int e = 0; e < 8; ++e) sg[mi][ni][e] = pack2(sigmoidf_(ag[mi][ni][2 * e]), sigmoidf_(ag[mi][ni][2 * e + 1]));
	s_add_u32 m0, s96, 32768
	s_nop 0
	global_load_lds_dwordx4 v205, s[56:57] offset:0
	global_load_lds_dwordx4 v206, s[56:57] offset:1024
	global_load_lds_dwordx4 v207, s[56:57] offset:2048
	global_load_lds_dwordx4 v208, s[56:57] offset:3072
	s_add_u32 m0, s96, 49152
	s_nop 0
	global_load_lds_dwordx4 v205, s[58:59] offset:0
	global_load_lds_dwordx4 v206, s[58:59] offset:1024
	global_load_lds_dwordx4 v207, s[58:59] offset:2048
	global_load_lds_dwordx4 v208, s[58:59] offset:3072
	s_add_u32 s56, s56, 128
	s_addc_u32 s57, s57, 0
	s_add_u32 s58, s58, 128
	s_addc_u32 s59, s59, 0
	ds_read_b128 v[130:133], v209 offset:0
	ds_read_b128 v[138:141], v213 offset:0
	ds_read_b128 v[142:145], v213 offset:4096
	ds_read_b128 v[134:137], v209 offset:4096
	ds_read_b128 v[146:149], v210 offset:0
	ds_read_b128 v[154:157], v214 offset:0
	ds_read_b128 v[158:161], v214 offset:4096
	ds_read_b128 v[150:153], v210 offset:4096
	s_waitcnt lgkmcnt(6)
	v_mfma_f32_32x32x16_bf16 v[114:129], v[130:133], v[138:141], v[114:129]
	v_mul_f32_e32 v28, 0xbfb8aa3b, v29
	v_exp_f32_e32 v28, v28
	s_waitcnt lgkmcnt(5)
	v_mfma_f32_32x32x16_bf16 v[98:113], v[130:133], v[142:145], v[98:113]
	v_cvt_pk_bf16_f32 v23, v23, v42
	s_waitcnt lgkmcnt(4)
	v_mfma_f32_32x32x16_bf16 v[82:97], v[134:137], v[138:141], v[82:97]
	v_mfma_f32_32x32x16_bf16 v[50:65], v[134:137], v[142:145], v[50:65]
	ds_read_b128 v[130:133], v211 offset:0
	ds_read_b128 v[138:141], v215 offset:0
	ds_read_b128 v[142:145], v215 offset:4096
	ds_read_b128 v[134:137], v211 offset:4096
	s_waitcnt lgkmcnt(6)
	v_mfma_f32_32x32x16_bf16 v[114:129], v[146:149], v[154:157], v[114:129]
	s_waitcnt lgkmcnt(5)
	v_mfma_f32_32x32x16_bf16 v[98:113], v[146:149], v[158:161], v[98:113]
	s_waitcnt lgkmcnt(4)
	v_mfma_f32_32x32x16_bf16 v[82:97], v[150:153], v[154:157], v[82:97]
	v_mfma_f32_32x32x16_bf16 v[50:65], v[150:153], v[158:161], v[50:65]
	ds_read_b128 v[146:149], v212 offset:0
	ds_read_b128 v[154:157], v216 offset:0
	ds_read_b128 v[158:161], v216 offset:4096
	ds_read_b128 v[150:153], v212 offset:4096
	s_waitcnt lgkmcnt(6)
	v_mfma_f32_32x32x16_bf16 v[114:129], v[130:133], v[138:141], v[114:129]
	s_waitcnt lgkmcnt(5)
	v_mfma_f32_32x32x16_bf16 v[98:113], v[130:133], v[142:145], v[98:113]
	s_waitcnt lgkmcnt(4)
	v_mfma_f32_32x32x16_bf16 v[82:97], v[134:137], v[138:141], v[82:97]
	v_mfma_f32_32x32x16_bf16 v[50:65], v[134:137], v[142:145], v[50:65]
	s_waitcnt lgkmcnt(2)
	v_mfma_f32_32x32x16_bf16 v[114:129], v[146:149], v[154:157], v[114:129]
	s_waitcnt lgkmcnt(1)
	v_mfma_f32_32x32x16_bf16 v[98:113], v[146:149], v[158:161], v[98:113]
	s_waitcnt lgkmcnt(0)
	v_mfma_f32_32x32x16_bf16 v[82:97], v[150:153], v[154:157], v[82:97]
	v_mfma_f32_32x32x16_bf16 v[50:65], v[150:153], v[158:161], v[50:65]
	s_waitcnt vmcnt(0)
	s_barrier
	ds_read_b128 v[130:133], v209 offset:32768
	ds_read_b128 v[138:141], v213 offset:32768
	ds_read_b128 v[142:145], v213 offset:36864
	ds_read_b128 v[134:137], v209 offset:36864
	ds_read_b128 v[146:149], v210 offset:32768
	ds_read_b128 v[154:157], v214 offset:32768
	ds_read_b128 v[158:161], v214 offset:36864
	ds_read_b128 v[150:153], v210 offset:36864
	s_waitcnt lgkmcnt(6)
	v_mfma_f32_32x32x16_bf16 v[114:129], v[130:133], v[138:141], v[114:129]
	s_waitcnt lgkmcnt(5)
	v_mfma_f32_32x32x16_bf16 v[98:113], v[130:133], v[142:145], v[98:113]
	s_waitcnt lgkmcnt(4)
	v_mfma_f32_32x32x16_bf16 v[82:97], v[134:137], v[138:141], v[82:97]
	v_mfma_f32_32x32x16_bf16 v[50:65], v[134:137], v[142:145], v[50:65]
	ds_read_b128 v[130:133], v211 offset:32768
	ds_read_b128 v[138:141], v215 offset:32768
	ds_read_b128 v[142:145], v215 offset:36864
	ds_read_b128 v[134:137], v211 offset:36864
	s_waitcnt lgkmcnt(6)
	v_mfma_f32_32x32x16_bf16 v[114:129], v[146:149], v[154:157], v[114:129]
	s_waitcnt lgkmcnt(5)
	v_mfma_f32_32x32x16_bf16 v[98:113], v[146:149], v[158:161], v[98:113]
	s_waitcnt lgkmcnt(4)
	v_mfma_f32_32x32x16_bf16 v[82:97], v[150:153], v[154:157], v[82:97]
	v_mfma_f32_32x32x16_bf16 v[50:65], v[150:153], v[158:161], v[50:65]
	ds_read_b128 v[146:149], v212 offset:32768
	ds_read_b128 v[154:157], v216 offset:32768
	ds_read_b128 v[158:161], v216 offset:36864
	ds_read_b128 v[150:153], v212 offset:36864
	s_waitcnt lgkmcnt(6)
	v_mfma_f32_32x32x16_bf16 v[114:129], v[130:133], v[138:141], v[114:129]
	s_waitcnt lgkmcnt(5)
	v_mfma_f32_32x32x16_bf16 v[98:113], v[130:133], v[142:145], v[98:113]
	s_waitcnt lgkmcnt(4)
	v_mfma_f32_32x32x16_bf16 v[82:97], v[134:137], v[138:141], v[82:97]
	v_mfma_f32_32x32x16_bf16 v[50:65], v[134:137], v[142:145], v[50:65]
	s_waitcnt lgkmcnt(2)
	v_mfma_f32_32x32x16_bf16 v[114:129], v[146:149], v[154:157], v[114:129]
	s_waitcnt lgkmcnt(1)
	v_mfma_f32_32x32x16_bf16 v[98:113], v[146:149], v[158:161], v[98:113]
	s_waitcnt lgkmcnt(0)
; __device__ __forceinline__ unsigned pack2(float a, float b) { f2_t f = {a, b}; return __builtin_bit_cast(unsigned, __builtin_convertvector(f, bf2_t)); }
; __device__ __forceinline__ float sigmoidf_(float x) { return __builtin_amdgcn_rcpf(1.f + fexp(-x)); }
; __device__ __forceinline__ void merge_tile(const Params& p, int mt, int nt, bf16* sA, bf16* sB) {
;     ...
;       for (int mi = 0; mi < 2; ++mi)
; #pragma unroll
;         for (int ni = 0; ni < 2; ++ni)
; #pragma unroll
;           for (int e = 0; e < 8; ++e) sg[mi][ni][e] = pack2(sigmoidf_(ag[mi][ni][2 * e]), sigmoidf_(ag[mi][ni][2 * e + 1]));
;     ...
; #pragma unroll
;     for (int mi = 0; mi < 2; ++mi)
; #pragma unroll
;       for (int ni = 0; ni < 2; ++ni)
; #pragma unroll
;         for (int e = 0; e < 8; ++e) {
;           const float v0 = __uint_as_float(mg[mi][ni][e] << 16) + __uint_as_float(sg[mi][ni][e] << 16) * ap[mi][ni][2 * e];
;           const float v1 = __uint_as_float(mg[mi][ni][e] & 0xffff0000u) + __uint_as_float(sg[mi][ni][e] & 0xffff0000u) * ap[mi][ni][2 * e + 1];
;           mg[mi][ni][e] = pack2(v0, v1);
;         }
	v_mfma_f32_32x32x16_bf16 v[82:97], v[150:153], v[154:157], v[82:97]
	v_mfma_f32_32x32x16_bf16 v[50:65], v[150:153], v[158:161], v[50:65]
	s_nop 15
	v_add_f32_e32 v134, 1.0, v28
	v_mul_f32_e32 v28, 0xbfb8aa3b, v30
	v_mul_f32_e32 v32, 0xbfb8aa3b, v32
	v_mul_f32_e32 v33, 0xbfb8aa3b, v33
	v_exp_f32_e32 v135, v28
	v_mul_f32_e32 v136, 0xbfb8aa3b, v31
	v_exp_f32_e32 v32, v32
	v_exp_f32_e32 v33, v33
	v_mul_f32_e32 v2, 0xbfb8aa3b, v2
	v_add_f32_e32 v32, 1.0, v32
	v_exp_f32_e32 v2, v2
	v_mul_f32_e32 v3, 0xbfb8aa3b, v3
	v_exp_f32_e32 v3, v3
	v_rcp_f32_e32 v134, v134
	v_add_f32_e32 v2, 1.0, v2
	v_mul_f32_e32 v12, 0xbfb8aa3b, v12
	v_add_f32_e32 v29, 1.0, v33
	v_rcp_f32_e32 v28, v32
	v_rcp_f32_e32 v29, v29
	v_cvt_pk_bf16_f32 v73, v73, v134
	s_add_i32 s3, s3, 1
	s_add_u32 s28, s28, 0x200000
	v_cvt_pk_bf16_f32 v32, v28, v29
	v_rcp_f32_e32 v28, v2
	v_add_f32_e32 v2, 1.0, v3
	v_mul_f32_e32 v3, 0xbfb8aa3b, v4
	v_exp_f32_e32 v3, v3
	v_mul_f32_e32 v4, 0xbfb8aa3b, v5
	v_exp_f32_e32 v4, v4
	v_rcp_f32_e32 v29, v2
	v_add_f32_e32 v2, 1.0, v3
	v_mul_f32_e32 v3, 0xbfb8aa3b, v6
	v_rcp_f32_e32 v30, v2
	v_exp_f32_e32 v24, v136
	v_add_f32_e32 v25, 1.0, v135
	v_rcp_f32_e32 v135, v25
	v_add_f32_e32 v2, 1.0, v4
	v_add_f32_e32 v24, 1.0, v24
	v_rcp_f32_e32 v136, v24
	v_exp_f32_e32 v3, v3
	v_mul_f32_e32 v4, 0xbfb8aa3b, v7
	v_exp_f32_e32 v4, v4
	v_rcp_f32_e32 v6, v2
	v_add_f32_e32 v2, 1.0, v3
	v_rcp_f32_e32 v7, v2
	v_add_f32_e32 v31, 1.0, v4
	v_rcp_f32_e32 v31, v31
	v_cvt_pk_bf16_f32 v33, v28, v29
	v_cvt_pk_bf16_f32 v78, v30, v6
	v_mul_f32_e32 v6, 0xbfb8aa3b, v8
	v_cvt_pk_bf16_f32 v79, v7, v31
	v_exp_f32_e32 v80, v6
	v_mul_f32_e32 v6, 0xbfb8aa3b, v9
	v_exp_f32_e32 v81, v6
	v_cvt_pk_bf16_f32 v134, v135, v136
	s_addc_u32 s29, s29, 0
	s_add_u32 s34, s34, 0x100000
	s_addc_u32 s35, s35, 0
	s_cmp_lg_u32 s3, 3
	v_add_f32_e32 v2, 1.0, v80
	v_rcp_f32_e32 v80, v2
	v_add_f32_e32 v2, 1.0, v81
	v_rcp_f32_e32 v81, v2
	v_mul_f32_e32 v2, 0xbfb8aa3b, v10
	v_exp_f32_e32 v10, v2
	v_mul_f32_e32 v0, 0xbfb8aa3b, v11
	v_exp_f32_e32 v0, v0
	v_add_f32_e32 v10, 1.0, v10
	v_rcp_f32_e32 v10, v10
	v_cvt_pk_bf16_f32 v11, v80, v81
	v_add_f32_e32 v0, 1.0, v0
	v_rcp_f32_e32 v0, v0
	v_mul_f32_e32 v7, 0xbfb8aa3b, v13
	v_exp_f32_e32 v6, v12
	v_exp_f32_e32 v7, v7
	v_mul_f32_e32 v8, 0xbfb8aa3b, v14
	v_mul_f32_e32 v9, 0xbfb8aa3b, v15
	v_exp_f32_e32 v8, v8
	v_exp_f32_e32 v9, v9
	v_mul_f32_e32 v12, 0xbfb8aa3b, v16
	v_mul_f32_e32 v13, 0xbfb8aa3b, v17
	v_add_f32_e32 v6, 1.0, v6
	v_add_f32_e32 v7, 1.0, v7
	v_exp_f32_e32 v12, v12
	v_exp_f32_e32 v13, v13
	v_rcp_f32_e32 v6, v6
	v_rcp_f32_e32 v7, v7
	v_add_f32_e32 v8, 1.0, v8
	v_add_f32_e32 v9, 1.0, v9
	v_rcp_f32_e32 v8, v8
	v_rcp_f32_e32 v9, v9
	v_cvt_pk_bf16_f32 v0, v10, v0
	v_add_f32_e32 v12, 1.0, v12
	v_lshlrev_b32_e32 v2, 16, v201
	v_lshlrev_b32_e32 v4, 16, v66
	v_and_b32_e32 v3, 0xffff0000, v201
	v_and_b32_e32 v5, 0xffff0000, v66
	v_fma_f32 v2, v114, v4, v2
	v_fma_f32 v3, v115, v5, v3
	v_lshlrev_b32_e32 v4, 16, v67
	v_cvt_pk_bf16_f32 v201, v2, v3
	v_lshlrev_b32_e32 v2, 16, v200
	v_and_b32_e32 v3, 0xffff0000, v200
	v_and_b32_e32 v5, 0xffff0000, v67
	v_pk_fma_f32 v[2:3], v[116:117], v[4:5], v[2:3]
	v_lshlrev_b32_e32 v4, 16, v68
	v_cvt_pk_bf16_f32 v200, v2, v3
	v_lshlrev_b32_e32 v2, 16, v199
	v_and_b32_e32 v3, 0xffff0000, v199
	v_and_b32_e32 v5, 0xffff0000, v68
	v_pk_fma_f32 v[2:3], v[118:119], v[4:5], v[2:3]
	v_lshlrev_b32_e32 v4, 16, v69
	v_cvt_pk_bf16_f32 v199, v2, v3
	v_lshlrev_b32_e32 v2, 16, v196
	v_and_b32_e32 v3, 0xffff0000, v196
	v_and_b32_e32 v5, 0xffff0000, v69
	v_pk_fma_f32 v[2:3], v[120:121], v[4:5], v[2:3]
	v_lshlrev_b32_e32 v4, 16, v70
	v_cvt_pk_bf16_f32 v196, v2, v3
	v_lshlrev_b32_e32 v2, 16, v193
	v_and_b32_e32 v3, 0xffff0000, v193
	v_and_b32_e32 v5, 0xffff0000, v70
	v_fma_f32 v2, v122, v4, v2
	v_fma_f32 v3, v123, v5, v3
	v_lshlrev_b32_e32 v4, 16, v71
	v_cvt_pk_bf16_f32 v193, v2, v3
	v_lshlrev_b32_e32 v2, 16, v192
	v_and_b32_e32 v3, 0xffff0000, v192
	v_and_b32_e32 v5, 0xffff0000, v71
	v_pk_fma_f32 v[2:3], v[124:125], v[4:5], v[2:3]
	v_lshlrev_b32_e32 v4, 16, v72
	v_cvt_pk_bf16_f32 v192, v2, v3
	v_lshlrev_b32_e32 v2, 16, v191
	v_and_b32_e32 v3, 0xffff0000, v191
	v_and_b32_e32 v5, 0xffff0000, v72
	v_pk_fma_f32 v[2:3], v[126:127], v[4:5], v[2:3]
	v_lshlrev_b32_e32 v4, 16, v34
	v_cvt_pk_bf16_f32 v191, v2, v3
	v_lshlrev_b32_e32 v2, 16, v190
	v_and_b32_e32 v3, 0xffff0000, v190
	v_and_b32_e32 v5, 0xffff0000, v34
	v_pk_fma_f32 v[2:3], v[128:129], v[4:5], v[2:3]
	v_lshlrev_b32_e32 v4, 16, v35
	v_cvt_pk_bf16_f32 v190, v2, v3
	v_lshlrev_b32_e32 v2, 16, v187
	v_and_b32_e32 v3, 0xffff0000, v187
	v_and_b32_e32 v5, 0xffff0000, v35
	v_pk_fma_f32 v[2:3], v[98:99], v[4:5], v[2:3]
	v_lshlrev_b32_e32 v4, 16, v36
	v_cvt_pk_bf16_f32 v187, v2, v3
	v_lshlrev_b32_e32 v2, 16, v189
	v_and_b32_e32 v3, 0xffff0000, v189
	v_and_b32_e32 v5, 0xffff0000, v36
	v_pk_fma_f32 v[2:3], v[100:101], v[4:5], v[2:3]
	v_lshlrev_b32_e32 v4, 16, v37
	v_cvt_pk_bf16_f32 v189, v2, v3
	v_lshlrev_b32_e32 v2, 16, v188
	v_and_b32_e32 v3, 0xffff0000, v188
	v_and_b32_e32 v5, 0xffff0000, v37
	v_pk_fma_f32 v[2:3], v[102:103], v[4:5], v[2:3]
	v_lshlrev_b32_e32 v4, 16, v38
	v_cvt_pk_bf16_f32 v188, v2, v3
	v_lshlrev_b32_e32 v2, 16, v186
	v_and_b32_e32 v3, 0xffff0000, v186
	v_and_b32_e32 v5, 0xffff0000, v38
	v_pk_fma_f32 v[2:3], v[104:105], v[4:5], v[2:3]
	v_lshlrev_b32_e32 v4, 16, v39
	v_cvt_pk_bf16_f32 v186, v2, v3
	v_lshlrev_b32_e32 v2, 16, v185
	v_and_b32_e32 v3, 0xffff0000, v185
	v_and_b32_e32 v5, 0xffff0000, v39
	v_pk_fma_f32 v[2:3], v[106:107], v[4:5], v[2:3]
	v_lshlrev_b32_e32 v4, 16, v40
	v_cvt_pk_bf16_f32 v185, v2, v3
	v_lshlrev_b32_e32 v2, 16, v184
	v_and_b32_e32 v3, 0xffff0000, v184
; __device__ __forceinline__ unsigned pack2(float a, float b) { f2_t f = {a, b}; return __builtin_bit_cast(unsigned, __builtin_convertvector(f, bf2_t)); }
; __device__ __forceinline__ void merge_tile(const Params& p, int mt, int nt, bf16* sA, bf16* sB) {
;     ...
; #pragma unroll
;     for (int mi = 0; mi < 2; ++mi)
; #pragma unroll
;       for (int ni = 0; ni < 2; ++ni)
; #pragma unroll
;         for (int e = 0; e < 8; ++e) {
;           const float v0 = __uint_as_float(mg[mi][ni][e] << 16) + __uint_as_float(sg[mi][ni][e] << 16) * ap[mi][ni][2 * e];
;           const float v1 = __uint_as_float(mg[mi][ni][e] & 0xffff0000u) + __uint_as_float(sg[mi][ni][e] & 0xffff0000u) * ap[mi][ni][2 * e + 1];
;           mg[mi][ni][e] = pack2(v0, v1);
;         }
;   }
; #pragma unroll
;   for (int mi = 0; mi < 2; ++mi)
; #pragma unroll
;     for (int ni = 0; ni < 2; ++ni)
; #pragma unroll
;       for (int e = 0; e < 16; ++e) {
;         const int t = m0 + wm * 64 + mi * 32 + ROW_OF(e, hh);
;         p.merged[(size_t)t * DM + n0 + wn * 64 + ni * 32 + r] = (bf16)((e & 1) ? (mg[mi][ni][e >> 1] >> 16) : (mg[mi][ni][e >> 1] & 0xffffu));
;       }
	v_and_b32_e32 v5, 0xffff0000, v40
	v_pk_fma_f32 v[2:3], v[108:109], v[4:5], v[2:3]
	v_lshlrev_b32_e32 v4, 16, v41
	v_cvt_pk_bf16_f32 v184, v2, v3
	v_lshlrev_b32_e32 v2, 16, v183
	v_and_b32_e32 v3, 0xffff0000, v183
	v_and_b32_e32 v5, 0xffff0000, v41
	v_pk_fma_f32 v[2:3], v[110:111], v[4:5], v[2:3]
	v_lshlrev_b32_e32 v4, 16, v18
	v_cvt_pk_bf16_f32 v183, v2, v3
	v_lshlrev_b32_e32 v2, 16, v182
	v_and_b32_e32 v3, 0xffff0000, v182
	v_and_b32_e32 v5, 0xffff0000, v18
	v_pk_fma_f32 v[2:3], v[112:113], v[4:5], v[2:3]
	v_lshlrev_b32_e32 v4, 16, v19
	v_cvt_pk_bf16_f32 v182, v2, v3
	v_lshlrev_b32_e32 v2, 16, v181
	v_and_b32_e32 v3, 0xffff0000, v181
	v_and_b32_e32 v5, 0xffff0000, v19
	v_pk_fma_f32 v[2:3], v[82:83], v[4:5], v[2:3]
	v_lshlrev_b32_e32 v4, 16, v20
	v_cvt_pk_bf16_f32 v181, v2, v3
	v_lshlrev_b32_e32 v2, 16, v180
	v_and_b32_e32 v3, 0xffff0000, v180
	v_and_b32_e32 v5, 0xffff0000, v20
	v_pk_fma_f32 v[2:3], v[84:85], v[4:5], v[2:3]
	v_lshlrev_b32_e32 v4, 16, v21
	v_cvt_pk_bf16_f32 v180, v2, v3
	v_lshlrev_b32_e32 v2, 16, v179
	v_and_b32_e32 v3, 0xffff0000, v179
	v_and_b32_e32 v5, 0xffff0000, v21
	v_pk_fma_f32 v[2:3], v[86:87], v[4:5], v[2:3]
	v_lshlrev_b32_e32 v4, 16, v22
	v_cvt_pk_bf16_f32 v179, v2, v3
	v_lshlrev_b32_e32 v2, 16, v178
	v_and_b32_e32 v3, 0xffff0000, v178
	v_and_b32_e32 v5, 0xffff0000, v22
	v_pk_fma_f32 v[2:3], v[88:89], v[4:5], v[2:3]
	v_lshlrev_b32_e32 v4, 16, v23
	v_cvt_pk_bf16_f32 v178, v2, v3
	v_lshlrev_b32_e32 v2, 16, v177
	v_and_b32_e32 v3, 0xffff0000, v177
	v_and_b32_e32 v5, 0xffff0000, v23
	v_pk_fma_f32 v[2:3], v[90:91], v[4:5], v[2:3]
	v_lshlrev_b32_e32 v4, 16, v73
	v_cvt_pk_bf16_f32 v177, v2, v3
	v_lshlrev_b32_e32 v2, 16, v176
	v_and_b32_e32 v3, 0xffff0000, v176
	v_and_b32_e32 v5, 0xffff0000, v73
	v_pk_fma_f32 v[2:3], v[92:93], v[4:5], v[2:3]
	v_lshlrev_b32_e32 v4, 16, v134
	v_cvt_pk_bf16_f32 v176, v2, v3
	v_lshlrev_b32_e32 v2, 16, v175
	v_and_b32_e32 v3, 0xffff0000, v175
	v_and_b32_e32 v5, 0xffff0000, v134
	v_pk_fma_f32 v[2:3], v[94:95], v[4:5], v[2:3]
	v_lshlrev_b32_e32 v4, 16, v32
	v_cvt_pk_bf16_f32 v175, v2, v3
	v_lshlrev_b32_e32 v2, 16, v174
	v_and_b32_e32 v3, 0xffff0000, v174
	v_and_b32_e32 v5, 0xffff0000, v32
	v_pk_fma_f32 v[2:3], v[96:97], v[4:5], v[2:3]
	v_lshlrev_b32_e32 v4, 16, v33
	v_cvt_pk_bf16_f32 v174, v2, v3
	v_lshlrev_b32_e32 v2, 16, v170
	v_and_b32_e32 v3, 0xffff0000, v170
	v_and_b32_e32 v5, 0xffff0000, v33
	v_pk_fma_f32 v[2:3], v[50:51], v[4:5], v[2:3]
	v_lshlrev_b32_e32 v4, 16, v78
	v_cvt_pk_bf16_f32 v170, v2, v3
	v_lshlrev_b32_e32 v2, 16, v172
	v_and_b32_e32 v3, 0xffff0000, v172
	v_and_b32_e32 v5, 0xffff0000, v78
	v_pk_fma_f32 v[2:3], v[52:53], v[4:5], v[2:3]
	v_lshlrev_b32_e32 v4, 16, v79
	v_cvt_pk_bf16_f32 v172, v2, v3
	v_lshlrev_b32_e32 v2, 16, v171
	v_and_b32_e32 v3, 0xffff0000, v171
	v_and_b32_e32 v5, 0xffff0000, v79
	v_pk_fma_f32 v[2:3], v[54:55], v[4:5], v[2:3]
	v_lshlrev_b32_e32 v4, 16, v11
	v_cvt_pk_bf16_f32 v171, v2, v3
	v_lshlrev_b32_e32 v2, 16, v169
	v_and_b32_e32 v3, 0xffff0000, v169
	v_and_b32_e32 v5, 0xffff0000, v11
	v_pk_fma_f32 v[2:3], v[56:57], v[4:5], v[2:3]
	v_add_f32_e32 v13, 1.0, v13
	v_cvt_pk_bf16_f32 v169, v2, v3
	v_lshlrev_b32_e32 v2, 16, v168
	v_lshlrev_b32_e32 v4, 16, v0
	v_and_b32_e32 v3, 0xffff0000, v168
	v_and_b32_e32 v5, 0xffff0000, v0
	v_rcp_f32_e32 v12, v12
	v_rcp_f32_e32 v13, v13
	v_cvt_pk_bf16_f32 v6, v6, v7
	v_pk_fma_f32 v[2:3], v[58:59], v[4:5], v[2:3]
	v_lshlrev_b32_e32 v4, 16, v6
	v_cvt_pk_bf16_f32 v168, v2, v3
	v_lshlrev_b32_e32 v2, 16, v167
	v_and_b32_e32 v3, 0xffff0000, v167
	v_and_b32_e32 v5, 0xffff0000, v6
	v_cvt_pk_bf16_f32 v7, v8, v9
	v_pk_fma_f32 v[2:3], v[60:61], v[4:5], v[2:3]
	v_lshlrev_b32_e32 v4, 16, v7
	v_cvt_pk_bf16_f32 v167, v2, v3
	v_lshlrev_b32_e32 v2, 16, v166
	v_and_b32_e32 v3, 0xffff0000, v166
	v_and_b32_e32 v5, 0xffff0000, v7
	v_cvt_pk_bf16_f32 v8, v12, v13
	v_pk_fma_f32 v[2:3], v[62:63], v[4:5], v[2:3]
	v_lshlrev_b32_e32 v4, 16, v8
	v_cvt_pk_bf16_f32 v166, v2, v3
	v_lshlrev_b32_e32 v2, 16, v173
	v_and_b32_e32 v3, 0xffff0000, v173
	v_and_b32_e32 v5, 0xffff0000, v8
	v_pk_fma_f32 v[2:3], v[64:65], v[4:5], v[2:3]
	s_nop 0
	v_cvt_pk_bf16_f32 v173, v2, v3
	s_cbranch_scc1 .LBB0_1067
	v_lshrrev_b32_e32 v4, 3, v197
	v_ashrrev_i32_e32 v2, 1, v198
	v_and_or_b32 v4, v4, 4, s2
	s_lshl_b64 s[2:3], s[20:21], 1
	v_readlane_b32 s20, v252, 15
	v_and_b32_e32 v2, 0xffffffc0, v2
	v_readlane_b32 s26, v252, 21
	v_and_b32_e32 v0, 64, v198
	v_add_u32_e32 v2, v4, v2
	v_readlane_b32 s27, v252, 22
	s_add_u32 s2, s26, s2
	v_and_b32_e32 v3, 31, v197
	s_addc_u32 s3, s27, s3
	v_lshlrev_b32_e32 v0, 1, v0
	v_or_b32_e32 v8, 1, v2
	v_or_b32_e32 v10, 2, v2
	v_or_b32_e32 v12, 3, v2
	v_or_b32_e32 v14, 8, v2
	v_or_b32_e32 v16, 9, v2
	v_or_b32_e32 v18, 10, v2
	v_or_b32_e32 v20, 11, v2
	v_or_b32_e32 v22, 16, v2
	v_or_b32_e32 v24, 17, v2
	v_or_b32_e32 v26, 18, v2
	v_or_b32_e32 v28, 19, v2
	v_or_b32_e32 v30, 24, v2
	v_or_b32_e32 v32, 25, v2
	v_or_b32_e32 v34, 26, v2
	v_or_b32_e32 v36, 27, v2
	v_lshl_add_u64 v[4:5], s[2:3], 0, v[0:1]
	v_lshlrev_b32_e32 v0, 1, v3
	v_ashrrev_i32_e32 v3, 31, v2
	v_ashrrev_i32_e32 v9, 31, v8
	v_ashrrev_i32_e32 v11, 31, v10
	v_ashrrev_i32_e32 v13, 31, v12
	v_ashrrev_i32_e32 v15, 31, v14
	v_ashrrev_i32_e32 v17, 31, v16
	v_ashrrev_i32_e32 v19, 31, v18
	v_ashrrev_i32_e32 v21, 31, v20
	v_ashrrev_i32_e32 v23, 31, v22
	v_ashrrev_i32_e32 v25, 31, v24
	v_ashrrev_i32_e32 v27, 31, v26
	v_ashrrev_i32_e32 v29, 31, v28
	v_ashrrev_i32_e32 v31, 31, v30
	v_ashrrev_i32_e32 v33, 31, v32
	v_ashrrev_i32_e32 v35, 31, v34
	v_ashrrev_i32_e32 v37, 31, v36
	v_lshl_add_u64 v[4:5], v[4:5], 0, v[0:1]
	v_lshlrev_b64 v[6:7], 11, v[2:3]
	v_lshlrev_b64 v[8:9], 11, v[8:9]
; __device__ __forceinline__ void merge_tile(const Params& p, int mt, int nt, bf16* sA, bf16* sB) {
;     ...
; #pragma unroll
;   for (int mi = 0; mi < 2; ++mi)
; #pragma unroll
;     for (int ni = 0; ni < 2; ++ni)
; #pragma unroll
;       for (int e = 0; e < 16; ++e) {
;         const int t = m0 + wm * 64 + mi * 32 + ROW_OF(e, hh);
;         p.merged[(size_t)t * DM + n0 + wn * 64 + ni * 32 + r] = (bf16)((e & 1) ? (mg[mi][ni][e >> 1] >> 16) : (mg[mi][ni][e >> 1] & 0xffffu));
;       }
	v_lshlrev_b64 v[10:11], 11, v[10:11]
	v_lshlrev_b64 v[12:13], 11, v[12:13]
	v_lshlrev_b64 v[14:15], 11, v[14:15]
	v_lshlrev_b64 v[16:17], 11, v[16:17]
	v_lshlrev_b64 v[18:19], 11, v[18:19]
	v_lshlrev_b64 v[20:21], 11, v[20:21]
	v_lshlrev_b64 v[22:23], 11, v[22:23]
	v_lshlrev_b64 v[24:25], 11, v[24:25]
	v_lshlrev_b64 v[26:27], 11, v[26:27]
	v_lshlrev_b64 v[28:29], 11, v[28:29]
	v_lshlrev_b64 v[30:31], 11, v[30:31]
	v_lshlrev_b64 v[32:33], 11, v[32:33]
	v_lshlrev_b64 v[34:35], 11, v[34:35]
	v_lshlrev_b64 v[36:37], 11, v[36:37]
	v_lshl_add_u64 v[6:7], v[4:5], 0, v[6:7]
	v_lshl_add_u64 v[8:9], v[4:5], 0, v[8:9]
	v_lshl_add_u64 v[10:11], v[4:5], 0, v[10:11]
	v_lshl_add_u64 v[12:13], v[4:5], 0, v[12:13]
	v_lshl_add_u64 v[14:15], v[4:5], 0, v[14:15]
	v_lshl_add_u64 v[16:17], v[4:5], 0, v[16:17]
	v_lshl_add_u64 v[18:19], v[4:5], 0, v[18:19]
	v_lshl_add_u64 v[20:21], v[4:5], 0, v[20:21]
	v_lshl_add_u64 v[22:23], v[4:5], 0, v[22:23]
	v_lshl_add_u64 v[24:25], v[4:5], 0, v[24:25]
	v_lshl_add_u64 v[26:27], v[4:5], 0, v[26:27]
	v_lshl_add_u64 v[28:29], v[4:5], 0, v[28:29]
	v_lshl_add_u64 v[30:31], v[4:5], 0, v[30:31]
	v_lshl_add_u64 v[32:33], v[4:5], 0, v[32:33]
	v_lshl_add_u64 v[34:35], v[4:5], 0, v[34:35]
	v_lshl_add_u64 v[36:37], v[4:5], 0, v[36:37]
	global_store_short v[6:7], v201, off
	global_store_short_d16_hi v[8:9], v201, off
	global_store_short v[10:11], v200, off
	global_store_short_d16_hi v[12:13], v200, off
	global_store_short v[14:15], v199, off
	global_store_short_d16_hi v[16:17], v199, off
	global_store_short v[18:19], v196, off
	global_store_short_d16_hi v[20:21], v196, off
	global_store_short v[22:23], v193, off
	global_store_short_d16_hi v[24:25], v193, off
	global_store_short v[26:27], v192, off
	global_store_short_d16_hi v[28:29], v192, off
	global_store_short v[30:31], v191, off
	global_store_short_d16_hi v[32:33], v191, off
	global_store_short v[34:35], v190, off
	global_store_short_d16_hi v[36:37], v190, off
	global_store_short v[6:7], v187, off offset:64
	global_store_short_d16_hi v[8:9], v187, off offset:64
	global_store_short v[10:11], v189, off offset:64
	global_store_short_d16_hi v[12:13], v189, off offset:64
	global_store_short v[14:15], v188, off offset:64
	global_store_short_d16_hi v[16:17], v188, off offset:64
	global_store_short v[18:19], v186, off offset:64
	global_store_short_d16_hi v[20:21], v186, off offset:64
	global_store_short v[22:23], v185, off offset:64
	global_store_short_d16_hi v[24:25], v185, off offset:64
	global_store_short v[26:27], v184, off offset:64
	global_store_short_d16_hi v[28:29], v184, off offset:64
	global_store_short v[30:31], v183, off offset:64
	global_store_short_d16_hi v[32:33], v183, off offset:64
	global_store_short v[34:35], v182, off offset:64
	global_store_short_d16_hi v[36:37], v182, off offset:64
	v_or_b32_e32 v6, 32, v2
	v_or_b32_e32 v8, 33, v2
	v_or_b32_e32 v10, 34, v2
	v_or_b32_e32 v12, 35, v2
	v_or_b32_e32 v14, 40, v2
	v_or_b32_e32 v16, 41, v2
	v_or_b32_e32 v18, 42, v2
	v_or_b32_e32 v20, 43, v2
	v_or_b32_e32 v22, 48, v2
	v_or_b32_e32 v24, 49, v2
	v_or_b32_e32 v26, 50, v2
	v_or_b32_e32 v28, 51, v2
	v_or_b32_e32 v30, 56, v2
	v_or_b32_e32 v32, 57, v2
	v_or_b32_e32 v34, 58, v2
	v_or_b32_e32 v2, 59, v2
	v_ashrrev_i32_e32 v7, 31, v6
	v_ashrrev_i32_e32 v9, 31, v8
	v_ashrrev_i32_e32 v11, 31, v10
	v_ashrrev_i32_e32 v13, 31, v12
	v_ashrrev_i32_e32 v15, 31, v14
	v_ashrrev_i32_e32 v17, 31, v16
	v_ashrrev_i32_e32 v19, 31, v18
	v_ashrrev_i32_e32 v21, 31, v20
	v_ashrrev_i32_e32 v23, 31, v22
	v_ashrrev_i32_e32 v25, 31, v24
	v_ashrrev_i32_e32 v27, 31, v26
	v_ashrrev_i32_e32 v29, 31, v28
	v_ashrrev_i32_e32 v31, 31, v30
	v_ashrrev_i32_e32 v33, 31, v32
	v_ashrrev_i32_e32 v35, 31, v34
	v_ashrrev_i32_e32 v3, 31, v2
	v_readlane_b32 s2, v254, 60
	v_lshlrev_b64 v[6:7], 11, v[6:7]
	v_lshlrev_b64 v[8:9], 11, v[8:9]
	v_lshlrev_b64 v[10:11], 11, v[10:11]
	v_lshlrev_b64 v[12:13], 11, v[12:13]
	v_lshlrev_b64 v[14:15], 11, v[14:15]
	v_lshlrev_b64 v[16:17], 11, v[16:17]
	v_lshlrev_b64 v[18:19], 11, v[18:19]
	v_lshlrev_b64 v[20:21], 11, v[20:21]
	v_lshlrev_b64 v[22:23], 11, v[22:23]
	v_lshlrev_b64 v[24:25], 11, v[24:25]
	v_lshlrev_b64 v[26:27], 11, v[26:27]
	v_lshlrev_b64 v[28:29], 11, v[28:29]
	v_lshlrev_b64 v[30:31], 11, v[30:31]
	v_lshlrev_b64 v[32:33], 11, v[32:33]
	v_lshlrev_b64 v[34:35], 11, v[34:35]
	v_lshlrev_b64 v[2:3], 11, v[2:3]
	s_add_i32 s0, s0, s2
	v_lshl_add_u64 v[6:7], v[4:5], 0, v[6:7]
	v_lshl_add_u64 v[8:9], v[4:5], 0, v[8:9]
	v_lshl_add_u64 v[10:11], v[4:5], 0, v[10:11]
	v_lshl_add_u64 v[12:13], v[4:5], 0, v[12:13]
	v_lshl_add_u64 v[14:15], v[4:5], 0, v[14:15]
	v_lshl_add_u64 v[16:17], v[4:5], 0, v[16:17]
	v_lshl_add_u64 v[18:19], v[4:5], 0, v[18:19]
	v_lshl_add_u64 v[20:21], v[4:5], 0, v[20:21]
	v_lshl_add_u64 v[22:23], v[4:5], 0, v[22:23]
	v_lshl_add_u64 v[24:25], v[4:5], 0, v[24:25]
	v_lshl_add_u64 v[26:27], v[4:5], 0, v[26:27]
	v_lshl_add_u64 v[28:29], v[4:5], 0, v[28:29]
	v_lshl_add_u64 v[30:31], v[4:5], 0, v[30:31]
	v_lshl_add_u64 v[32:33], v[4:5], 0, v[32:33]
	v_lshl_add_u64 v[34:35], v[4:5], 0, v[34:35]
	v_lshl_add_u64 v[2:3], v[4:5], 0, v[2:3]
	s_cmpk_gt_u32 s0, 0xff
	v_readlane_b32 s21, v252, 16
	v_readlane_b32 s22, v252, 17
	v_readlane_b32 s23, v252, 18
	v_readlane_b32 s24, v252, 19
	v_readlane_b32 s25, v252, 20
	global_store_short v[6:7], v181, off
	global_store_short_d16_hi v[8:9], v181, off
	global_store_short v[10:11], v180, off
	global_store_short_d16_hi v[12:13], v180, off
	global_store_short v[14:15], v179, off
	global_store_short_d16_hi v[16:17], v179, off
	global_store_short v[18:19], v178, off
	global_store_short_d16_hi v[20:21], v178, off
	global_store_short v[22:23], v177, off
	global_store_short_d16_hi v[24:25], v177, off
	global_store_short v[26:27], v176, off
	global_store_short_d16_hi v[28:29], v176, off
	global_store_short v[30:31], v175, off
	global_store_short_d16_hi v[32:33], v175, off
	global_store_short v[34:35], v174, off
	global_store_short_d16_hi v[2:3], v174, off
	global_store_short v[6:7], v170, off offset:64
	global_store_short_d16_hi v[8:9], v170, off offset:64
	global_store_short v[10:11], v172, off offset:64
	global_store_short_d16_hi v[12:13], v172, off offset:64
	global_store_short v[14:15], v171, off offset:64
	global_store_short_d16_hi v[16:17], v171, off offset:64
	global_store_short v[18:19], v169, off offset:64
	global_store_short_d16_hi v[20:21], v169, off offset:64
	global_store_short v[22:23], v168, off offset:64
	global_store_short_d16_hi v[24:25], v168, off offset:64
	global_store_short v[26:27], v167, off offset:64
	global_store_short_d16_hi v[28:29], v167, off offset:64
	global_store_short v[30:31], v166, off offset:64
	global_store_short_d16_hi v[32:33], v166, off offset:64
	global_store_short v[34:35], v173, off offset:64
	global_store_short_d16_hi v[2:3], v173, off offset:64
	s_cbranch_scc0 .LBB0_1066
